# P5 in-proj GEMM epilogue: the out/ws pointer pair kept resident in s[94:97] for the phase instead of 44 kernarg s_load + wait round trips in the store cascade
# baseline (speedup 1.0000x reference)
; #define PG8_WAIT_V(n) asm volatile("s_waitcnt vmcnt(" #n ")" ::: "memory")
; #define PG8_BAR __builtin_amdgcn_s_barrier()
; template <class Epi, class Sched, bool ALIGN_EPI = false, bool SP2 = false, bool F8 = false>
; __device__ __forceinline__ void gemm_phase(PG8_LAS unsigned char* lds, const Gemm g, const Sched& S, const Epi& E) {
;     ...
;     const char* cA = (const char*)g.A + (size_t)cur.pm * tstep + (size_t)cur.kofs * 2; const char* cB = (const char*)g.Bt + (size_t)cur.pn * tstep + (size_t)cur.kofs * 2;
;     S.a_ready(cur);
;     if constexpr (SP2) {
;         PG8_STAGE(PG8_SB(0, 0), cB, voffB); PG8_STAGE(PG8_SB(0, 1), cB + hstep, voffB); PG8_STAGE(PG8_SA(0, 0), cA, voffA); PG8_STAGE(PG8_SA(0, 1), cA + hstep, voffA);
;         if (wr == 1) PG8_BAR;
;         PG8_WAIT_V(2); PG8_BAR;
;         PG8_STAGE(PG8_SB(1, 0), cB + kstep, voffB); PG8_STAGE(PG8_SA(1, 0), cA + kstep, voffA); PG8_STAGE(PG8_SB(1, 1), cB + hstep + kstep, voffB);
;         PG8_WAIT_V(6); PG8_BAR;
;     } else {
;         PG8_STAGE(PG8_SB(0, 0), cB, voffB); PG8_STAGE(PG8_SA(0, 0), cA, voffA); PG8_STAGE(PG8_SB(0, 1), cB + hstep, voffB); PG8_STAGE(PG8_SA(0, 1), cA + hstep, voffA);
;         if (wr == 1) PG8_BAR;
;         PG8_WAIT_V(4); PG8_BAR;
;         PG8_STAGE(PG8_SB(1, 0), cB + kstep, voffB); PG8_STAGE(PG8_SA(1, 0), cA + kstep, voffA); PG8_STAGE(PG8_SB(1, 1), cB + hstep + kstep, voffB);
;         PG8_WAIT_V(6); PG8_BAR;
; __device__ __forceinline__ void route_in(unsigned char* ws, float* out, float qscale, int row, int c, f32x4 v0, f32x4 v1) {
;     const int pn = c >> 8; const bool smp = row >= MPc; const int sb = (row - MPc) >> 6, ts = row & 63;
;     if (pn >= 6 && pn < 8) { v0 = v0 * qscale; v1 = v1 * qscale; }
;     u32x4 w; w.x = cvt_pk_bf16(v0[0], v0[1]); w.y = cvt_pk_bf16(v0[2], v0[3]); w.z = cvt_pk_bf16(v1[0], v1[1]); w.w = cvt_pk_bf16(v1[2], v1[3]);
;     if (pn < 2) { *(u32x4*)((bf16_t*)(ws + WS_Z) + (size_t)row * 512 + c) = w; }
;     else if (pn < 6) { const int cc = c - 512; *(u32x4*)((bf16_t*)(ws + WS_XBC) + (size_t)row * 1024 + cc) = w;
;         if (!smp) { const int tt = row & 4095; if (tt >= 4093) { float* p = out + O_CONVP + (size_t)((row >> 12) * 3 + tt - 4093) * 1024 + cc; *(f32x4*)p = v0; *(f32x4*)(p + 4) = v1; } }
;         else if (ts >= 61) { float* p = out + O_CONVS + (size_t)(sb * 3 + ts - 61) * 1024 + cc; *(f32x4*)p = v0; *(f32x4*)(p + 4) = v1; } }
.LBB0_457:
	s_load_dwordx4 s[12:15], s[58:59], 0xf0
	s_load_dwordx2 s[94:95], s[58:59], 0xf0
	s_load_dwordx2 s[96:97], s[58:59], 0xf8
	v_readlane_b32 s1, v254, 6
	s_ashr_i32 s66, s69, 31
	s_ashr_i32 s67, s1, 31
	s_waitcnt vmcnt(2)
	s_waitcnt lgkmcnt(0)
	s_add_u32 s34, s14, 0xb000000
	s_addc_u32 s35, s15, 0
	s_add_u32 s36, s14, 0x6f00000
	s_addc_u32 s37, s15, 0
	s_add_u32 s38, s12, 0x10400000
	s_addc_u32 s39, s13, 0
	s_add_u32 s40, s12, 0x10818000
	s_addc_u32 s41, s13, 0
	s_lshl_b32 s3, s9, 5
	s_and_b32 s69, s3, 0x60
	s_lshl_b32 s68, s10, 6
	s_lshl_b32 s1, s10, 13
	s_lshl_b32 s3, s69, 7
	s_add_u32 s10, s6, 0x80
	s_addc_u32 s11, s7, 0
	s_add_u32 s12, s6, 0x20080
	s_addc_u32 s13, s7, 0
	v_lshl_add_u64 v[2:3], s[10:11], 0, v[134:135]
	s_add_i32 m0, s55, 0x18000
	s_barrier
	global_load_lds_dwordx4 v[2:3], off
	s_add_i32 m0, s55, 0x1a000
	s_add_u32 s10, s4, 0x80
	s_addc_u32 s11, s5, 0
	v_lshl_add_u64 v[2:3], s[12:13], 0, v[134:135]
	s_add_u32 s12, s4, 0x20080
	s_addc_u32 s13, s5, 0
	s_add_i32 s70, s55, 0x8000
	s_add_i32 s71, s55, 0xa000
	global_load_lds_dwordx4 v[2:3], off
	v_lshl_add_u64 v[2:3], s[10:11], 0, v[132:133]
	s_add_u32 s10, s6, 0x40080
	s_mov_b32 m0, s70
	s_addc_u32 s11, s7, 0
	global_load_lds_dwordx4 v[2:3], off
	v_lshl_add_u64 v[2:3], s[12:13], 0, v[132:133]
	s_mov_b32 m0, s71
	s_add_u32 s12, s6, 0x60080
	global_load_lds_dwordx4 v[2:3], off
	s_addc_u32 s13, s7, 0
	v_lshl_add_u64 v[2:3], s[10:11], 0, v[134:135]
	s_add_i32 m0, s55, 0x1c000
	v_and_b32_e32 v1, 48, v0
	global_load_lds_dwordx4 v[2:3], off
	v_lshl_add_u64 v[2:3], s[12:13], 0, v[134:135]
	s_add_i32 m0, s55, 0x1e000
	s_movk_i32 s9, 0x3c0
	global_load_lds_dwordx4 v[2:3], off
	v_lshlrev_b32_e32 v2, 6, v0
	v_lshlrev_b32_e32 v0, 2, v0
	v_and_or_b32 v1, v2, s9, v1
	v_and_b32_e32 v0, 32, v0
	s_waitcnt vmcnt(6)
	s_cmpk_lt_u32 s8, 0x100
	v_bitop3_b32 v2, v1, s1, v0 bitop3:0xde
	v_bitop3_b32 v164, s3, v1, v0 bitop3:0xf6
	s_cselect_b64 s[50:51], -1, 0
	s_add_i32 s73, 0, 0x10000
	s_add_i32 s74, 0, 0x14000
	s_mov_b64 s[42:43], 0x80
	s_mov_b64 s[44:45], 0x20080
	s_mov_b32 s72, 0x8000
	s_mov_b64 s[46:47], 0x40080
	s_mov_b64 s[48:49], 0x60080
	v_mov_b32_e32 v136, s2
	v_mov_b32_e32 v158, s0
	v_mov_b64_e32 v[0:1], s[6:7]
	v_mov_b64_e32 v[130:131], s[4:5]
	v_mov_b64_e32 v[138:139], 0x600
	v_mov_b64_e32 v[140:141], 0x5ff
	s_mov_b64 s[52:53], 0x100
	v_add_u32_e32 v165, s73, v164
	v_add_u32_e32 v166, s74, v164
	v_add_u32_e32 v167, 0, v2
	s_mov_b32 s75, 0x2080000
	s_mov_b32 s76, 0x4106000
	s_movk_i32 s77, 0x7fff
	s_movk_i32 s78, 0x880
	s_mov_b32 s54, 0x3e38aa3b
	s_movk_i32 s79, 0xfff
	s_movk_i32 s80, 0xffc
	s_barrier
	s_branch .LBB0_460

; __device__ __forceinline__ unsigned cvt_pk_bf16(float lo, float hi) { unsigned r; asm volatile("v_cvt_pk_bf16_f32 %0, %1, %2" : "=v"(r) : "v"(lo), "v"(hi)); return r; }
; __device__ __forceinline__ void route_in(unsigned char* ws, float* out, float qscale, int row, int c, f32x4 v0, f32x4 v1) {
;     const int pn = c >> 8; const bool smp = row >= MPc; const int sb = (row - MPc) >> 6, ts = row & 63;
;     if (pn >= 6 && pn < 8) { v0 = v0 * qscale; v1 = v1 * qscale; }
;     u32x4 w; w.x = cvt_pk_bf16(v0[0], v0[1]); w.y = cvt_pk_bf16(v0[2], v0[3]); w.z = cvt_pk_bf16(v1[0], v1[1]); w.w = cvt_pk_bf16(v1[2], v1[3]);
;     if (pn < 2) { *(u32x4*)((bf16_t*)(ws + WS_Z) + (size_t)row * 512 + c) = w; }
;     else if (pn < 6) { const int cc = c - 512; *(u32x4*)((bf16_t*)(ws + WS_XBC) + (size_t)row * 1024 + cc) = w;
;         if (!smp) { const int tt = row & 4095; if (tt >= 4093) { float* p = out + O_CONVP + (size_t)((row >> 12) * 3 + tt - 4093) * 1024 + cc; *(f32x4*)p = v0; *(f32x4*)(p + 4) = v1; } }
;         else if (ts >= 61) { float* p = out + O_CONVS + (size_t)(sb * 3 + ts - 61) * 1024 + cc; *(f32x4*)p = v0; *(f32x4*)(p + 4) = v1; } }
;     else if (pn < 8) { const int cc = c - 1536; const size_t qrow = smp ? (size_t)(MPc + sb * 256 + ts) : (size_t)row; *(u32x4*)((bf16_t*)(ws + WS_Q) + qrow * 512 + cc) = w; }
;     else { const bool isk = pn < 10; const int cc = c - (isk ? 2048 : 2560);
;         bf16_t* bp = smp ? (bf16_t*)(ws + (isk ? WS_KS : WS_VS)) + (size_t)(sb * 2176 + 2048 + ts) * 512 + cc : (bf16_t*)(ws + (isk ? WS_K : WS_V)) + (size_t)row * 512 + cc;
;         *(u32x4*)bp = w;
;         float* fp = smp ? out + (isk ? O_NKS : O_NVS) + (size_t)(row - MPc) * 512 + cc : out + (isk ? O_NKP : O_NVP) + (size_t)row * 512 + cc;
;         *(f32x4*)fp = v0; *(f32x4*)(fp + 4) = v1; }
.LBB0_466:
	v_mov_b32_e32 v128, v252
	v_lshlrev_b32_e32 v130, 8, v158
	v_and_b32_e32 v143, 15, v128
	v_lshlrev_b32_e32 v129, 8, v136
	v_lshrrev_b32_e32 v128, 1, v128
	v_add_u32_e32 v145, s68, v130
	v_and_or_b32 v128, v128, 24, v129
	v_cmp_gt_u32_e32 vcc, 10, v136
	v_or_b32_e32 v160, v143, v145
	v_or_b32_e32 v150, s69, v128
	s_and_b64 s[4:5], vcc, exec
	v_add_u32_e32 v128, 0xffff8000, v160
	v_ashrrev_i32_e32 v161, 31, v160
	v_cmp_lt_i32_e64 s[10:11], s77, v160
	s_movk_i32 s4, 0xf800
	v_ashrrev_i32_e32 v130, 6, v128
	v_or_b32_e32 v153, 0x8000, v143
	v_cndmask_b32_e64 v129, v161, 0, s[10:11]
	v_cndmask_b32_e64 v128, v160, v128, s[10:11]
	s_cselect_b32 s56, s4, 0xfffff600
	s_mov_b32 s4, 0xf300000
	v_lshlrev_b64 v[158:159], 11, v[128:129]
	v_lshl_add_u32 v128, v130, 8, v153
	s_cselect_b32 s81, s4, 0x12200000
	s_mov_b32 s4, 0x14200000
	s_cselect_b32 s83, s75, 0x3080000
	s_cselect_b32 s84, s76, 0x4146000
	v_or_b32_e32 v152, 0x800, v143
	v_cndmask_b32_e64 v128, v160, v128, s[10:11]
	v_cmp_lt_i32_e64 s[2:3], 7, v136
	v_and_b32_e32 v151, 0xfffffe, v136
	v_cmp_lt_i32_e64 s[6:7], 1, v136
	v_cmp_lt_u32_e64 s[12:13], 5, v136
	s_cselect_b32 s82, s4, 0x15300000
	v_mad_u64_u32 v[162:163], s[4:5], v130, s78, v[152:153]
	v_mov_b32_e32 v131, s83
	v_mov_b32_e32 v136, s84
	v_ashrrev_i32_e32 v129, 31, v128
	v_cndmask_b32_e64 v163, v131, v136, s[10:11]
	v_lshlrev_b64 v[156:157], 10, v[128:129]
	v_pk_mul_f32 v[168:169], v[126:127], s[54:55] op_sel_hi:[1,0]
	v_pk_mul_f32 v[170:171], v[124:125], s[54:55] op_sel_hi:[1,0]
	v_pk_mul_f32 v[130:131], v[122:123], s[54:55] op_sel_hi:[1,0]
	v_pk_mul_f32 v[128:129], v[120:121], s[54:55] op_sel_hi:[1,0]
	v_cmp_eq_u32_e64 s[4:5], 6, v151
	v_lshlrev_b64 v[154:155], 11, v[160:161]
	s_mov_b64 s[8:9], -1
	v_cndmask_b32_e64 v129, v121, v129, s[4:5]
	v_cndmask_b32_e64 v128, v120, v128, s[4:5]
	v_cndmask_b32_e64 v131, v123, v131, s[4:5]
	v_cndmask_b32_e64 v130, v122, v130, s[4:5]
	v_cndmask_b32_e64 v125, v125, v171, s[4:5]
	v_cndmask_b32_e64 v124, v124, v170, s[4:5]
	v_cndmask_b32_e64 v127, v127, v169, s[4:5]
	v_cndmask_b32_e64 v126, v126, v168, s[4:5]
	s_and_b64 vcc, exec, s[6:7]
	v_cvt_pk_bf16_f32 v120, v124, v125
	v_cvt_pk_bf16_f32 v121, v126, v127
	v_cvt_pk_bf16_f32 v122, v128, v129
	v_cvt_pk_bf16_f32 v123, v130, v131
	s_cbranch_vccz .LBB0_476
	s_and_b64 vcc, exec, s[12:13]
	s_cbranch_vccz .LBB0_473
	s_and_b64 vcc, exec, s[2:3]
	s_cbranch_vccz .LBB0_470
	s_mov_b64 s[88:89], s[94:95]
	s_mov_b64 s[90:91], s[96:97]
	v_cndmask_b32_e64 v170, v160, v162, s[10:11]
	v_mov_b32_e32 v136, s81
	v_mov_b32_e32 v151, s82
	v_cndmask_b32_e64 v136, v136, v151, s[10:11]
	v_ashrrev_i32_e32 v171, 31, v170
	v_add_u32_e32 v168, s56, v150
	s_waitcnt lgkmcnt(0)
	v_lshl_add_u64 v[172:173], s[90:91], 0, v[136:137]
	v_lshlrev_b64 v[170:171], 10, v[170:171]
	v_lshl_add_u64 v[170:171], v[172:173], 0, v[170:171]
	v_ashrrev_i32_e32 v169, 31, v168
	v_lshl_add_u64 v[170:171], v[168:169], 1, v[170:171]
	v_lshlrev_b32_e32 v136, 2, v163
	global_store_dwordx4 v[170:171], v[120:123], off
	v_lshl_add_u64 v[170:171], s[88:89], 0, v[136:137]
	v_lshl_add_u64 v[170:171], v[170:171], 0, v[158:159]
	v_lshl_add_u64 v[168:169], v[168:169], 2, v[170:171]
	global_store_dwordx4 v[168:169], v[124:127], off
	global_store_dwordx4 v[168:169], v[128:131], off offset:16
	s_mov_b64 s[8:9], 0
.LBB0_470:
	s_andn2_b64 vcc, exec, s[8:9]
	s_cbranch_vccnz .LBB0_472
	s_mov_b64 s[88:89], s[94:95]
	s_mov_b64 s[90:91], s[96:97]
	v_mov_b32_e32 v151, v137
	s_waitcnt lgkmcnt(0)
	v_lshl_add_u64 v[124:125], s[90:91], 0, v[156:157]
	v_lshl_add_u64 v[124:125], v[150:151], 1, v[124:125]
	v_add_co_u32_e32 v124, vcc, 0xd0ff000, v124
	s_nop 1
	v_addc_co_u32_e32 v125, vcc, 0, v125, vcc
	global_store_dwordx4 v[124:125], v[120:123], off offset:1024

; __device__ __forceinline__ void route_in(unsigned char* ws, float* out, float qscale, int row, int c, f32x4 v0, f32x4 v1) {
;     ...
;     else if (pn < 6) { const int cc = c - 512; *(u32x4*)((bf16_t*)(ws + WS_XBC) + (size_t)row * 1024 + cc) = w;
.LBB0_473:
	s_andn2_b64 vcc, exec, s[8:9]
	s_cbranch_vccnz .LBB0_475
	s_mov_b64 s[88:89], s[94:95]
	s_mov_b64 s[90:91], s[96:97]
	v_mov_b32_e32 v151, v137
	s_waitcnt lgkmcnt(0)
	v_lshl_add_u64 v[124:125], s[90:91], 0, v[154:155]
	v_lshl_add_u64 v[124:125], v[150:151], 1, v[124:125]
	v_add_co_u32_e32 v124, vcc, 0x6eff000, v124
	s_nop 1
	v_addc_co_u32_e32 v125, vcc, 0, v125, vcc
	global_store_dwordx4 v[124:125], v[120:123], off offset:3072

; __device__ __forceinline__ unsigned cvt_pk_bf16(float lo, float hi) { unsigned r; asm volatile("v_cvt_pk_bf16_f32 %0, %1, %2" : "=v"(r) : "v"(lo), "v"(hi)); return r; }
; __device__ __forceinline__ void route_in(unsigned char* ws, float* out, float qscale, int row, int c, f32x4 v0, f32x4 v1) {
;     const int pn = c >> 8; const bool smp = row >= MPc; const int sb = (row - MPc) >> 6, ts = row & 63;
;     if (pn >= 6 && pn < 8) { v0 = v0 * qscale; v1 = v1 * qscale; }
;     u32x4 w; w.x = cvt_pk_bf16(v0[0], v0[1]); w.y = cvt_pk_bf16(v0[2], v0[3]); w.z = cvt_pk_bf16(v1[0], v1[1]); w.w = cvt_pk_bf16(v1[2], v1[3]);
;     if (pn < 2) { *(u32x4*)((bf16_t*)(ws + WS_Z) + (size_t)row * 512 + c) = w; }
;     else if (pn < 6) { const int cc = c - 512; *(u32x4*)((bf16_t*)(ws + WS_XBC) + (size_t)row * 1024 + cc) = w;
;         if (!smp) { const int tt = row & 4095; if (tt >= 4093) { float* p = out + O_CONVP + (size_t)((row >> 12) * 3 + tt - 4093) * 1024 + cc; *(f32x4*)p = v0; *(f32x4*)(p + 4) = v1; } }
;         else if (ts >= 61) { float* p = out + O_CONVS + (size_t)(sb * 3 + ts - 61) * 1024 + cc; *(f32x4*)p = v0; *(f32x4*)(p + 4) = v1; } }
;     else if (pn < 8) { const int cc = c - 1536; const size_t qrow = smp ? (size_t)(MPc + sb * 256 + ts) : (size_t)row; *(u32x4*)((bf16_t*)(ws + WS_Q) + qrow * 512 + cc) = w; }
;     else { const bool isk = pn < 10; const int cc = c - (isk ? 2048 : 2560);
;         bf16_t* bp = smp ? (bf16_t*)(ws + (isk ? WS_KS : WS_VS)) + (size_t)(sb * 2176 + 2048 + ts) * 512 + cc : (bf16_t*)(ws + (isk ? WS_K : WS_V)) + (size_t)row * 512 + cc;
;         *(u32x4*)bp = w;
;         float* fp = smp ? out + (isk ? O_NKS : O_NVS) + (size_t)(row - MPc) * 512 + cc : out + (isk ? O_NKP : O_NVP) + (size_t)row * 512 + cc;
;         *(f32x4*)fp = v0; *(f32x4*)(fp + 4) = v1; }
;     __device__ __forceinline__ void operator()(const f32x4 (&acc)[2][2][4][2], const Unit& u, int wr, int wc, int fr, int fq) const {
;     ...
;                 for (int bj = 0; bj < 2; ++bj) route_in(ws, out, qscale, row, colt + bj * HALF, acc[ai][bj][m][0], acc[ai][bj][m][1]); }
.LBB0_478:
	v_pk_mul_f32 v[126:127], v[118:119], s[54:55] op_sel_hi:[1,0]
	v_pk_mul_f32 v[128:129], v[116:117], s[54:55] op_sel_hi:[1,0]
	v_cndmask_b32_e64 v118, v118, v126, s[4:5]
	v_cndmask_b32_e64 v126, 0, 1, s[6:7]
	v_pk_mul_f32 v[120:121], v[114:115], s[54:55] op_sel_hi:[1,0]
	v_pk_mul_f32 v[130:131], v[112:113], s[54:55] op_sel_hi:[1,0]
	v_cmp_ne_u32_e64 s[8:9], 1, v126
	v_cndmask_b32_e64 v126, 0, 1, s[12:13]
	v_cndmask_b32_e64 v123, v115, v121, s[4:5]
	v_cndmask_b32_e64 v122, v114, v120, s[4:5]
	v_cndmask_b32_e64 v121, v113, v131, s[4:5]
	v_cndmask_b32_e64 v120, v112, v130, s[4:5]
	v_cndmask_b32_e64 v119, v119, v127, s[4:5]
	v_cndmask_b32_e64 v117, v117, v129, s[4:5]
	v_cndmask_b32_e64 v116, v116, v128, s[4:5]
	s_mov_b64 s[14:15], -1
	s_andn2_b64 vcc, exec, s[6:7]
	v_cmp_ne_u32_e64 s[6:7], 1, v126
	v_cvt_pk_bf16_f32 v112, v116, v117
	v_cvt_pk_bf16_f32 v113, v118, v119
	v_cvt_pk_bf16_f32 v114, v120, v121
	v_cvt_pk_bf16_f32 v115, v122, v123
	s_cbranch_vccnz .LBB0_488
	s_and_b64 vcc, exec, s[6:7]
	s_mov_b64 s[12:13], -1
	s_cbranch_vccnz .LBB0_485
	s_andn2_b64 vcc, exec, s[2:3]
	s_cbranch_vccnz .LBB0_482
	s_mov_b64 s[12:13], s[94:95]
	s_mov_b64 s[14:15], s[96:97]
	v_cndmask_b32_e64 v126, v160, v162, s[10:11]
	v_mov_b32_e32 v127, s81
	v_mov_b32_e32 v128, s82
	v_cndmask_b32_e64 v136, v127, v128, s[10:11]
	v_ashrrev_i32_e32 v127, 31, v126
	s_waitcnt lgkmcnt(0)
	v_lshl_add_u64 v[128:129], s[14:15], 0, v[136:137]
	v_lshlrev_b64 v[126:127], 10, v[126:127]
	s_ashr_i32 s57, s56, 31
	v_lshl_add_u64 v[126:127], v[128:129], 0, v[126:127]
	v_lshl_add_u64 v[128:129], v[150:151], 0, s[56:57]
	v_lshl_add_u64 v[126:127], v[128:129], 1, v[126:127]
	v_lshlrev_b32_e32 v136, 2, v163
	global_store_dwordx4 v[126:127], v[112:115], off offset:256
	v_lshl_add_u64 v[126:127], s[12:13], 0, v[136:137]
	v_lshl_add_u64 v[126:127], v[126:127], 0, v[158:159]
	v_lshl_add_u64 v[126:127], v[128:129], 2, v[126:127]
	s_mov_b64 s[12:13], 0
	global_store_dwordx4 v[126:127], v[116:119], off offset:512
	global_store_dwordx4 v[126:127], v[120:123], off offset:528
.LBB0_482:
	s_andn2_b64 vcc, exec, s[12:13]
	s_cbranch_vccnz .LBB0_484
	s_mov_b64 s[12:13], s[94:95]
	s_mov_b64 s[14:15], s[96:97]
	v_mov_b32_e32 v136, v150
	s_waitcnt lgkmcnt(0)
	v_lshl_add_u64 v[116:117], s[14:15], 0, v[156:157]
	v_lshl_add_u64 v[116:117], v[136:137], 1, v[116:117]
	v_add_co_u32_e32 v116, vcc, 0xd0ff000, v116
	s_nop 1
	v_addc_co_u32_e32 v117, vcc, 0, v117, vcc
	global_store_dwordx4 v[116:117], v[112:115], off offset:1280

; __device__ __forceinline__ void route_in(unsigned char* ws, float* out, float qscale, int row, int c, f32x4 v0, f32x4 v1) {
;     ...
;     else if (pn < 6) { const int cc = c - 512; *(u32x4*)((bf16_t*)(ws + WS_XBC) + (size_t)row * 1024 + cc) = w;
.LBB0_485:
	s_andn2_b64 vcc, exec, s[12:13]
	s_cbranch_vccnz .LBB0_487
	s_mov_b64 s[12:13], s[94:95]
	s_mov_b64 s[14:15], s[96:97]
	v_mov_b32_e32 v136, v150
	s_waitcnt lgkmcnt(0)
	v_lshl_add_u64 v[116:117], s[14:15], 0, v[154:155]
	v_lshl_add_u64 v[116:117], v[136:137], 1, v[116:117]
	v_add_co_u32_e32 v116, vcc, 0x6eff000, v116
	s_nop 1
	v_addc_co_u32_e32 v117, vcc, 0, v117, vcc
	global_store_dwordx4 v[116:117], v[112:115], off offset:3328

; __device__ __forceinline__ unsigned cvt_pk_bf16(float lo, float hi) { unsigned r; asm volatile("v_cvt_pk_bf16_f32 %0, %1, %2" : "=v"(r) : "v"(lo), "v"(hi)); return r; }
; __device__ __forceinline__ void route_in(unsigned char* ws, float* out, float qscale, int row, int c, f32x4 v0, f32x4 v1) {
;     const int pn = c >> 8; const bool smp = row >= MPc; const int sb = (row - MPc) >> 6, ts = row & 63;
;     if (pn >= 6 && pn < 8) { v0 = v0 * qscale; v1 = v1 * qscale; }
;     u32x4 w; w.x = cvt_pk_bf16(v0[0], v0[1]); w.y = cvt_pk_bf16(v0[2], v0[3]); w.z = cvt_pk_bf16(v1[0], v1[1]); w.w = cvt_pk_bf16(v1[2], v1[3]);
;     if (pn < 2) { *(u32x4*)((bf16_t*)(ws + WS_Z) + (size_t)row * 512 + c) = w; }
;     else if (pn < 6) { const int cc = c - 512; *(u32x4*)((bf16_t*)(ws + WS_XBC) + (size_t)row * 1024 + cc) = w;
;         if (!smp) { const int tt = row & 4095; if (tt >= 4093) { float* p = out + O_CONVP + (size_t)((row >> 12) * 3 + tt - 4093) * 1024 + cc; *(f32x4*)p = v0; *(f32x4*)(p + 4) = v1; } }
;         else if (ts >= 61) { float* p = out + O_CONVS + (size_t)(sb * 3 + ts - 61) * 1024 + cc; *(f32x4*)p = v0; *(f32x4*)(p + 4) = v1; } }
;     else if (pn < 8) { const int cc = c - 1536; const size_t qrow = smp ? (size_t)(MPc + sb * 256 + ts) : (size_t)row; *(u32x4*)((bf16_t*)(ws + WS_Q) + qrow * 512 + cc) = w; }
;     else { const bool isk = pn < 10; const int cc = c - (isk ? 2048 : 2560);
;         bf16_t* bp = smp ? (bf16_t*)(ws + (isk ? WS_KS : WS_VS)) + (size_t)(sb * 2176 + 2048 + ts) * 512 + cc : (bf16_t*)(ws + (isk ? WS_K : WS_V)) + (size_t)row * 512 + cc;
;         *(u32x4*)bp = w;
;         float* fp = smp ? out + (isk ? O_NKS : O_NVS) + (size_t)(row - MPc) * 512 + cc : out + (isk ? O_NKP : O_NVP) + (size_t)row * 512 + cc;
;         *(f32x4*)fp = v0; *(f32x4*)(fp + 4) = v1; }
;     __device__ __forceinline__ void operator()(const f32x4 (&acc)[2][2][4][2], const Unit& u, int wr, int wc, int fr, int fq) const {
;     ...
;         for (int ai = 0; ai < 2; ++ai)
; #pragma unroll
;             for (int m = 0; m < 4; ++m) { const int row = u.pm * BM + ai * HALF + wr * 64 + m * 16 + fr;
; #pragma unroll
;                 for (int bj = 0; bj < 2; ++bj) route_in(ws, out, qscale, row, colt + bj * HALF, acc[ai][bj][m][0], acc[ai][bj][m][1]); }
.LBB0_490:
	v_or_b32_e32 v128, 16, v143
	v_or_b32_e32 v124, v128, v145
	v_add_u32_e32 v112, 0xffff8000, v124
	v_ashrrev_i32_e32 v114, 6, v112
	v_or_b32_e32 v116, 0x810, v143
	v_or_b32_e32 v117, 0x8010, v143
	v_mad_u64_u32 v[126:127], s[10:11], v114, s78, v[116:117]
	v_ashrrev_i32_e32 v125, 31, v124
	v_cmp_lt_i32_e64 s[10:11], s77, v124
	v_mov_b32_e32 v115, s83
	v_mov_b32_e32 v118, s84
	v_cndmask_b32_e64 v113, v125, 0, s[10:11]
	v_cndmask_b32_e64 v112, v124, v112, s[10:11]
	v_lshlrev_b64 v[122:123], 11, v[112:113]
	v_lshl_add_u32 v112, v114, 8, v117
	v_cndmask_b32_e64 v112, v124, v112, s[10:11]
	v_ashrrev_i32_e32 v113, 31, v112
	v_lshlrev_b64 v[120:121], 10, v[112:113]
	v_pk_mul_f32 v[130:131], v[110:111], s[54:55] op_sel_hi:[1,0]
	v_pk_mul_f32 v[154:155], v[108:109], s[54:55] op_sel_hi:[1,0]
	v_pk_mul_f32 v[112:113], v[106:107], s[54:55] op_sel_hi:[1,0]
	v_pk_mul_f32 v[156:157], v[104:105], s[54:55] op_sel_hi:[1,0]
	v_cndmask_b32_e64 v127, v115, v118, s[10:11]
	v_lshlrev_b64 v[118:119], 11, v[124:125]
	v_cndmask_b32_e64 v115, v107, v113, s[4:5]
	v_cndmask_b32_e64 v114, v106, v112, s[4:5]
	v_cndmask_b32_e64 v113, v105, v157, s[4:5]
	v_cndmask_b32_e64 v112, v104, v156, s[4:5]
	v_cndmask_b32_e64 v111, v111, v131, s[4:5]
	v_cndmask_b32_e64 v110, v110, v130, s[4:5]
	v_cndmask_b32_e64 v109, v109, v155, s[4:5]
	v_cndmask_b32_e64 v108, v108, v154, s[4:5]
	s_and_b64 vcc, exec, s[8:9]
	s_mov_b64 s[12:13], -1
	v_cvt_pk_bf16_f32 v104, v108, v109
	v_cvt_pk_bf16_f32 v105, v110, v111
	v_cvt_pk_bf16_f32 v106, v112, v113
	v_cvt_pk_bf16_f32 v107, v114, v115
	s_cbranch_vccnz .LBB0_500
	s_and_b64 vcc, exec, s[6:7]
	s_cbranch_vccnz .LBB0_497
	s_andn2_b64 vcc, exec, s[2:3]
	s_cbranch_vccnz .LBB0_494
	s_mov_b64 s[12:13], s[94:95]
	s_mov_b64 s[14:15], s[96:97]
	v_cndmask_b32_e64 v154, v124, v126, s[10:11]
	v_mov_b32_e32 v129, s81
	v_mov_b32_e32 v131, s82
	v_cndmask_b32_e64 v136, v129, v131, s[10:11]
	v_ashrrev_i32_e32 v155, 31, v154
	v_add_u32_e32 v130, s56, v150
	s_waitcnt lgkmcnt(0)
	v_lshl_add_u64 v[156:157], s[14:15], 0, v[136:137]
	v_lshlrev_b64 v[154:155], 10, v[154:155]
	v_lshl_add_u64 v[154:155], v[156:157], 0, v[154:155]
	v_ashrrev_i32_e32 v131, 31, v130
	v_lshl_add_u64 v[154:155], v[130:131], 1, v[154:155]
	v_lshlrev_b32_e32 v136, 2, v127
	global_store_dwordx4 v[154:155], v[104:107], off
	v_lshl_add_u64 v[154:155], s[12:13], 0, v[136:137]
	v_lshl_add_u64 v[154:155], v[154:155], 0, v[122:123]
	v_lshl_add_u64 v[130:131], v[130:131], 2, v[154:155]
	s_mov_b64 s[12:13], 0
	global_store_dwordx4 v[130:131], v[108:111], off
	global_store_dwordx4 v[130:131], v[112:115], off offset:16
.LBB0_494:
	s_andn2_b64 vcc, exec, s[12:13]
	s_cbranch_vccnz .LBB0_496
	s_mov_b64 s[12:13], s[94:95]
	s_mov_b64 s[14:15], s[96:97]
	v_mov_b32_e32 v136, v150
	s_waitcnt lgkmcnt(0)
	v_lshl_add_u64 v[108:109], s[14:15], 0, v[120:121]
	v_lshl_add_u64 v[108:109], v[136:137], 1, v[108:109]
	v_add_co_u32_e32 v108, vcc, 0xd0ff000, v108
	s_nop 1
	v_addc_co_u32_e32 v109, vcc, 0, v109, vcc
	global_store_dwordx4 v[108:109], v[104:107], off offset:1024

; __device__ __forceinline__ void route_in(unsigned char* ws, float* out, float qscale, int row, int c, f32x4 v0, f32x4 v1) {
;     ...
;     else if (pn < 6) { const int cc = c - 512; *(u32x4*)((bf16_t*)(ws + WS_XBC) + (size_t)row * 1024 + cc) = w;
.LBB0_497:
	s_andn2_b64 vcc, exec, s[12:13]
	s_cbranch_vccnz .LBB0_499
	s_mov_b64 s[12:13], s[94:95]
	s_mov_b64 s[14:15], s[96:97]
	v_mov_b32_e32 v136, v150
	s_waitcnt lgkmcnt(0)
	v_lshl_add_u64 v[108:109], s[14:15], 0, v[118:119]
	v_lshl_add_u64 v[108:109], v[136:137], 1, v[108:109]
	v_add_co_u32_e32 v108, vcc, 0x6eff000, v108
	s_nop 1
	v_addc_co_u32_e32 v109, vcc, 0, v109, vcc
	global_store_dwordx4 v[108:109], v[104:107], off offset:3072

; __device__ __forceinline__ unsigned cvt_pk_bf16(float lo, float hi) { unsigned r; asm volatile("v_cvt_pk_bf16_f32 %0, %1, %2" : "=v"(r) : "v"(lo), "v"(hi)); return r; }
; __device__ __forceinline__ void route_in(unsigned char* ws, float* out, float qscale, int row, int c, f32x4 v0, f32x4 v1) {
;     const int pn = c >> 8; const bool smp = row >= MPc; const int sb = (row - MPc) >> 6, ts = row & 63;
;     if (pn >= 6 && pn < 8) { v0 = v0 * qscale; v1 = v1 * qscale; }
;     u32x4 w; w.x = cvt_pk_bf16(v0[0], v0[1]); w.y = cvt_pk_bf16(v0[2], v0[3]); w.z = cvt_pk_bf16(v1[0], v1[1]); w.w = cvt_pk_bf16(v1[2], v1[3]);
;     if (pn < 2) { *(u32x4*)((bf16_t*)(ws + WS_Z) + (size_t)row * 512 + c) = w; }
;     else if (pn < 6) { const int cc = c - 512; *(u32x4*)((bf16_t*)(ws + WS_XBC) + (size_t)row * 1024 + cc) = w;
;         if (!smp) { const int tt = row & 4095; if (tt >= 4093) { float* p = out + O_CONVP + (size_t)((row >> 12) * 3 + tt - 4093) * 1024 + cc; *(f32x4*)p = v0; *(f32x4*)(p + 4) = v1; } }
;         else if (ts >= 61) { float* p = out + O_CONVS + (size_t)(sb * 3 + ts - 61) * 1024 + cc; *(f32x4*)p = v0; *(f32x4*)(p + 4) = v1; } }
;     else if (pn < 8) { const int cc = c - 1536; const size_t qrow = smp ? (size_t)(MPc + sb * 256 + ts) : (size_t)row; *(u32x4*)((bf16_t*)(ws + WS_Q) + qrow * 512 + cc) = w; }
;     else { const bool isk = pn < 10; const int cc = c - (isk ? 2048 : 2560);
;         bf16_t* bp = smp ? (bf16_t*)(ws + (isk ? WS_KS : WS_VS)) + (size_t)(sb * 2176 + 2048 + ts) * 512 + cc : (bf16_t*)(ws + (isk ? WS_K : WS_V)) + (size_t)row * 512 + cc;
;         *(u32x4*)bp = w;
;         float* fp = smp ? out + (isk ? O_NKS : O_NVS) + (size_t)(row - MPc) * 512 + cc : out + (isk ? O_NKP : O_NVP) + (size_t)row * 512 + cc;
;         *(f32x4*)fp = v0; *(f32x4*)(fp + 4) = v1; }
;     __device__ __forceinline__ void operator()(const f32x4 (&acc)[2][2][4][2], const Unit& u, int wr, int wc, int fr, int fq) const {
;     ...
;                 for (int bj = 0; bj < 2; ++bj) route_in(ws, out, qscale, row, colt + bj * HALF, acc[ai][bj][m][0], acc[ai][bj][m][1]); }
.LBB0_502:
	v_pk_mul_f32 v[110:111], v[102:103], s[54:55] op_sel_hi:[1,0]
	v_pk_mul_f32 v[112:113], v[100:101], s[54:55] op_sel_hi:[1,0]
	v_pk_mul_f32 v[104:105], v[98:99], s[54:55] op_sel_hi:[1,0]
	v_pk_mul_f32 v[114:115], v[96:97], s[54:55] op_sel_hi:[1,0]
	v_cndmask_b32_e64 v107, v99, v105, s[4:5]
	v_cndmask_b32_e64 v106, v98, v104, s[4:5]
	v_cndmask_b32_e64 v105, v97, v115, s[4:5]
	v_cndmask_b32_e64 v104, v96, v114, s[4:5]
	v_cndmask_b32_e64 v103, v103, v111, s[4:5]
	v_cndmask_b32_e64 v102, v102, v110, s[4:5]
	v_cndmask_b32_e64 v101, v101, v113, s[4:5]
	v_cndmask_b32_e64 v100, v100, v112, s[4:5]
	s_and_b64 vcc, exec, s[8:9]
	s_mov_b64 s[12:13], -1
	v_cvt_pk_bf16_f32 v96, v100, v101
	v_cvt_pk_bf16_f32 v97, v102, v103
	v_cvt_pk_bf16_f32 v98, v104, v105
	v_cvt_pk_bf16_f32 v99, v106, v107
	s_cbranch_vccnz .LBB0_512
	s_and_b64 vcc, exec, s[6:7]
	s_cbranch_vccnz .LBB0_509
	s_andn2_b64 vcc, exec, s[2:3]
	s_cbranch_vccnz .LBB0_506
	s_mov_b64 s[12:13], s[94:95]
	s_mov_b64 s[14:15], s[96:97]
	v_cndmask_b32_e64 v110, v124, v126, s[10:11]
	v_mov_b32_e32 v111, s81
	v_mov_b32_e32 v112, s82
	v_cndmask_b32_e64 v136, v111, v112, s[10:11]
	v_ashrrev_i32_e32 v111, 31, v110
	s_waitcnt lgkmcnt(0)
	v_lshl_add_u64 v[112:113], s[14:15], 0, v[136:137]
	v_lshlrev_b64 v[110:111], 10, v[110:111]
	s_ashr_i32 s57, s56, 31
	v_lshl_add_u64 v[110:111], v[112:113], 0, v[110:111]
	v_lshl_add_u64 v[112:113], v[150:151], 0, s[56:57]
	v_lshl_add_u64 v[110:111], v[112:113], 1, v[110:111]
	v_lshlrev_b32_e32 v136, 2, v127
	global_store_dwordx4 v[110:111], v[96:99], off offset:256
	v_lshl_add_u64 v[110:111], s[12:13], 0, v[136:137]
	v_lshl_add_u64 v[110:111], v[110:111], 0, v[122:123]
	v_lshl_add_u64 v[110:111], v[112:113], 2, v[110:111]
	s_mov_b64 s[12:13], 0
	global_store_dwordx4 v[110:111], v[100:103], off offset:512
	global_store_dwordx4 v[110:111], v[104:107], off offset:528
.LBB0_506:
	s_andn2_b64 vcc, exec, s[12:13]
	s_cbranch_vccnz .LBB0_508
	s_mov_b64 s[12:13], s[94:95]
	s_mov_b64 s[14:15], s[96:97]
	v_mov_b32_e32 v136, v150
	s_waitcnt lgkmcnt(0)
	v_lshl_add_u64 v[100:101], s[14:15], 0, v[120:121]
	v_lshl_add_u64 v[100:101], v[136:137], 1, v[100:101]
	v_add_co_u32_e32 v100, vcc, 0xd0ff000, v100
	s_nop 1
	v_addc_co_u32_e32 v101, vcc, 0, v101, vcc
	global_store_dwordx4 v[100:101], v[96:99], off offset:1280

; __device__ __forceinline__ void route_in(unsigned char* ws, float* out, float qscale, int row, int c, f32x4 v0, f32x4 v1) {
;     ...
;     else if (pn < 6) { const int cc = c - 512; *(u32x4*)((bf16_t*)(ws + WS_XBC) + (size_t)row * 1024 + cc) = w;
.LBB0_509:
	s_andn2_b64 vcc, exec, s[12:13]
	s_cbranch_vccnz .LBB0_511
	s_mov_b64 s[12:13], s[94:95]
	s_mov_b64 s[14:15], s[96:97]
	v_mov_b32_e32 v136, v150
	s_waitcnt lgkmcnt(0)
	v_lshl_add_u64 v[100:101], s[14:15], 0, v[118:119]
	v_lshl_add_u64 v[100:101], v[136:137], 1, v[100:101]
	v_add_co_u32_e32 v100, vcc, 0x6eff000, v100
	s_nop 1
	v_addc_co_u32_e32 v101, vcc, 0, v101, vcc
	global_store_dwordx4 v[100:101], v[96:99], off offset:3328

; __device__ __forceinline__ unsigned cvt_pk_bf16(float lo, float hi) { unsigned r; asm volatile("v_cvt_pk_bf16_f32 %0, %1, %2" : "=v"(r) : "v"(lo), "v"(hi)); return r; }
; __device__ __forceinline__ void route_in(unsigned char* ws, float* out, float qscale, int row, int c, f32x4 v0, f32x4 v1) {
;     const int pn = c >> 8; const bool smp = row >= MPc; const int sb = (row - MPc) >> 6, ts = row & 63;
;     if (pn >= 6 && pn < 8) { v0 = v0 * qscale; v1 = v1 * qscale; }
;     u32x4 w; w.x = cvt_pk_bf16(v0[0], v0[1]); w.y = cvt_pk_bf16(v0[2], v0[3]); w.z = cvt_pk_bf16(v1[0], v1[1]); w.w = cvt_pk_bf16(v1[2], v1[3]);
;     if (pn < 2) { *(u32x4*)((bf16_t*)(ws + WS_Z) + (size_t)row * 512 + c) = w; }
;     else if (pn < 6) { const int cc = c - 512; *(u32x4*)((bf16_t*)(ws + WS_XBC) + (size_t)row * 1024 + cc) = w;
;         if (!smp) { const int tt = row & 4095; if (tt >= 4093) { float* p = out + O_CONVP + (size_t)((row >> 12) * 3 + tt - 4093) * 1024 + cc; *(f32x4*)p = v0; *(f32x4*)(p + 4) = v1; } }
;         else if (ts >= 61) { float* p = out + O_CONVS + (size_t)(sb * 3 + ts - 61) * 1024 + cc; *(f32x4*)p = v0; *(f32x4*)(p + 4) = v1; } }
;     else if (pn < 8) { const int cc = c - 1536; const size_t qrow = smp ? (size_t)(MPc + sb * 256 + ts) : (size_t)row; *(u32x4*)((bf16_t*)(ws + WS_Q) + qrow * 512 + cc) = w; }
;     else { const bool isk = pn < 10; const int cc = c - (isk ? 2048 : 2560);
;         bf16_t* bp = smp ? (bf16_t*)(ws + (isk ? WS_KS : WS_VS)) + (size_t)(sb * 2176 + 2048 + ts) * 512 + cc : (bf16_t*)(ws + (isk ? WS_K : WS_V)) + (size_t)row * 512 + cc;
;         *(u32x4*)bp = w;
;         float* fp = smp ? out + (isk ? O_NKS : O_NVS) + (size_t)(row - MPc) * 512 + cc : out + (isk ? O_NKP : O_NVP) + (size_t)row * 512 + cc;
;         *(f32x4*)fp = v0; *(f32x4*)(fp + 4) = v1; }
;     __device__ __forceinline__ void operator()(const f32x4 (&acc)[2][2][4][2], const Unit& u, int wr, int wc, int fr, int fq) const {
;     ...
;         for (int ai = 0; ai < 2; ++ai)
; #pragma unroll
;             for (int m = 0; m < 4; ++m) { const int row = u.pm * BM + ai * HALF + wr * 64 + m * 16 + fr;
; #pragma unroll
;                 for (int bj = 0; bj < 2; ++bj) route_in(ws, out, qscale, row, colt + bj * HALF, acc[ai][bj][m][0], acc[ai][bj][m][1]); }
.LBB0_514:
	v_or_b32_e32 v112, 32, v143
	v_or_b32_e32 v108, v112, v145
	v_add_u32_e32 v96, 0xffff8000, v108
	v_ashrrev_i32_e32 v98, 6, v96
	v_or_b32_e32 v100, 0x820, v143
	v_or_b32_e32 v101, 0x8020, v143
	v_mad_u64_u32 v[110:111], s[10:11], v98, s78, v[100:101]
	v_ashrrev_i32_e32 v109, 31, v108
	v_cmp_lt_i32_e64 s[10:11], s77, v108
	v_mov_b32_e32 v99, s83
	v_mov_b32_e32 v102, s84
	v_cndmask_b32_e64 v97, v109, 0, s[10:11]
	v_cndmask_b32_e64 v96, v108, v96, s[10:11]
	v_lshlrev_b64 v[106:107], 11, v[96:97]
	v_lshl_add_u32 v96, v98, 8, v101
	v_cndmask_b32_e64 v96, v108, v96, s[10:11]
	v_ashrrev_i32_e32 v97, 31, v96
	v_lshlrev_b64 v[104:105], 10, v[96:97]
	v_pk_mul_f32 v[114:115], v[94:95], s[54:55] op_sel_hi:[1,0]
	v_pk_mul_f32 v[118:119], v[92:93], s[54:55] op_sel_hi:[1,0]
	v_pk_mul_f32 v[96:97], v[90:91], s[54:55] op_sel_hi:[1,0]
	v_pk_mul_f32 v[120:121], v[88:89], s[54:55] op_sel_hi:[1,0]
	v_cndmask_b32_e64 v111, v99, v102, s[10:11]
	v_lshlrev_b64 v[102:103], 11, v[108:109]
	v_cndmask_b32_e64 v99, v91, v97, s[4:5]
	v_cndmask_b32_e64 v98, v90, v96, s[4:5]
	v_cndmask_b32_e64 v97, v89, v121, s[4:5]
	v_cndmask_b32_e64 v96, v88, v120, s[4:5]
	v_cndmask_b32_e64 v95, v95, v115, s[4:5]
	v_cndmask_b32_e64 v94, v94, v114, s[4:5]
	v_cndmask_b32_e64 v93, v93, v119, s[4:5]
	v_cndmask_b32_e64 v92, v92, v118, s[4:5]
	s_and_b64 vcc, exec, s[8:9]
	s_mov_b64 s[12:13], -1
	v_cvt_pk_bf16_f32 v88, v92, v93
	v_cvt_pk_bf16_f32 v89, v94, v95
	v_cvt_pk_bf16_f32 v90, v96, v97
	v_cvt_pk_bf16_f32 v91, v98, v99
	s_cbranch_vccnz .LBB0_524
	s_and_b64 vcc, exec, s[6:7]
	s_cbranch_vccnz .LBB0_521
	s_andn2_b64 vcc, exec, s[2:3]
	s_cbranch_vccnz .LBB0_518
	s_mov_b64 s[12:13], s[94:95]
	s_mov_b64 s[14:15], s[96:97]
	v_cndmask_b32_e64 v118, v108, v110, s[10:11]
	v_mov_b32_e32 v113, s81
	v_mov_b32_e32 v115, s82
	v_cndmask_b32_e64 v136, v113, v115, s[10:11]
	v_ashrrev_i32_e32 v119, 31, v118
	v_add_u32_e32 v114, s56, v150
	s_waitcnt lgkmcnt(0)
	v_lshl_add_u64 v[120:121], s[14:15], 0, v[136:137]
	v_lshlrev_b64 v[118:119], 10, v[118:119]
	v_lshl_add_u64 v[118:119], v[120:121], 0, v[118:119]
	v_ashrrev_i32_e32 v115, 31, v114
	v_lshl_add_u64 v[118:119], v[114:115], 1, v[118:119]
	v_lshlrev_b32_e32 v136, 2, v111
	global_store_dwordx4 v[118:119], v[88:91], off
	v_lshl_add_u64 v[118:119], s[12:13], 0, v[136:137]
	v_lshl_add_u64 v[118:119], v[118:119], 0, v[106:107]
	v_lshl_add_u64 v[114:115], v[114:115], 2, v[118:119]
	s_mov_b64 s[12:13], 0
	global_store_dwordx4 v[114:115], v[92:95], off
	global_store_dwordx4 v[114:115], v[96:99], off offset:16
.LBB0_518:
	s_andn2_b64 vcc, exec, s[12:13]
	s_cbranch_vccnz .LBB0_520
	s_mov_b64 s[12:13], s[94:95]
	s_mov_b64 s[14:15], s[96:97]
	v_mov_b32_e32 v136, v150
	s_waitcnt lgkmcnt(0)
	v_lshl_add_u64 v[92:93], s[14:15], 0, v[104:105]
	v_lshl_add_u64 v[92:93], v[136:137], 1, v[92:93]
	v_add_co_u32_e32 v92, vcc, 0xd0ff000, v92
	s_nop 1
	v_addc_co_u32_e32 v93, vcc, 0, v93, vcc
	global_store_dwordx4 v[92:93], v[88:91], off offset:1024

; __device__ __forceinline__ void route_in(unsigned char* ws, float* out, float qscale, int row, int c, f32x4 v0, f32x4 v1) {
;     ...
;     else if (pn < 6) { const int cc = c - 512; *(u32x4*)((bf16_t*)(ws + WS_XBC) + (size_t)row * 1024 + cc) = w;
.LBB0_521:
	s_andn2_b64 vcc, exec, s[12:13]
	s_cbranch_vccnz .LBB0_523
	s_mov_b64 s[12:13], s[94:95]
	s_mov_b64 s[14:15], s[96:97]
	v_mov_b32_e32 v136, v150
	s_waitcnt lgkmcnt(0)
	v_lshl_add_u64 v[92:93], s[14:15], 0, v[102:103]
	v_lshl_add_u64 v[92:93], v[136:137], 1, v[92:93]
	v_add_co_u32_e32 v92, vcc, 0x6eff000, v92
	s_nop 1
	v_addc_co_u32_e32 v93, vcc, 0, v93, vcc
	global_store_dwordx4 v[92:93], v[88:91], off offset:3072

; __device__ __forceinline__ unsigned cvt_pk_bf16(float lo, float hi) { unsigned r; asm volatile("v_cvt_pk_bf16_f32 %0, %1, %2" : "=v"(r) : "v"(lo), "v"(hi)); return r; }
; __device__ __forceinline__ void route_in(unsigned char* ws, float* out, float qscale, int row, int c, f32x4 v0, f32x4 v1) {
;     const int pn = c >> 8; const bool smp = row >= MPc; const int sb = (row - MPc) >> 6, ts = row & 63;
;     if (pn >= 6 && pn < 8) { v0 = v0 * qscale; v1 = v1 * qscale; }
;     u32x4 w; w.x = cvt_pk_bf16(v0[0], v0[1]); w.y = cvt_pk_bf16(v0[2], v0[3]); w.z = cvt_pk_bf16(v1[0], v1[1]); w.w = cvt_pk_bf16(v1[2], v1[3]);
;     if (pn < 2) { *(u32x4*)((bf16_t*)(ws + WS_Z) + (size_t)row * 512 + c) = w; }
;     else if (pn < 6) { const int cc = c - 512; *(u32x4*)((bf16_t*)(ws + WS_XBC) + (size_t)row * 1024 + cc) = w;
;         if (!smp) { const int tt = row & 4095; if (tt >= 4093) { float* p = out + O_CONVP + (size_t)((row >> 12) * 3 + tt - 4093) * 1024 + cc; *(f32x4*)p = v0; *(f32x4*)(p + 4) = v1; } }
;         else if (ts >= 61) { float* p = out + O_CONVS + (size_t)(sb * 3 + ts - 61) * 1024 + cc; *(f32x4*)p = v0; *(f32x4*)(p + 4) = v1; } }
;     else if (pn < 8) { const int cc = c - 1536; const size_t qrow = smp ? (size_t)(MPc + sb * 256 + ts) : (size_t)row; *(u32x4*)((bf16_t*)(ws + WS_Q) + qrow * 512 + cc) = w; }
;     else { const bool isk = pn < 10; const int cc = c - (isk ? 2048 : 2560);
;         bf16_t* bp = smp ? (bf16_t*)(ws + (isk ? WS_KS : WS_VS)) + (size_t)(sb * 2176 + 2048 + ts) * 512 + cc : (bf16_t*)(ws + (isk ? WS_K : WS_V)) + (size_t)row * 512 + cc;
;         *(u32x4*)bp = w;
;         float* fp = smp ? out + (isk ? O_NKS : O_NVS) + (size_t)(row - MPc) * 512 + cc : out + (isk ? O_NKP : O_NVP) + (size_t)row * 512 + cc;
;         *(f32x4*)fp = v0; *(f32x4*)(fp + 4) = v1; }
;     __device__ __forceinline__ void operator()(const f32x4 (&acc)[2][2][4][2], const Unit& u, int wr, int wc, int fr, int fq) const {
;     ...
;                 for (int bj = 0; bj < 2; ++bj) route_in(ws, out, qscale, row, colt + bj * HALF, acc[ai][bj][m][0], acc[ai][bj][m][1]); }
.LBB0_526:
	v_pk_mul_f32 v[94:95], v[86:87], s[54:55] op_sel_hi:[1,0]
	v_pk_mul_f32 v[96:97], v[84:85], s[54:55] op_sel_hi:[1,0]
	v_pk_mul_f32 v[88:89], v[82:83], s[54:55] op_sel_hi:[1,0]
	v_pk_mul_f32 v[98:99], v[80:81], s[54:55] op_sel_hi:[1,0]
	v_cndmask_b32_e64 v91, v83, v89, s[4:5]
	v_cndmask_b32_e64 v90, v82, v88, s[4:5]
	v_cndmask_b32_e64 v89, v81, v99, s[4:5]
	v_cndmask_b32_e64 v88, v80, v98, s[4:5]
	v_cndmask_b32_e64 v87, v87, v95, s[4:5]
	v_cndmask_b32_e64 v86, v86, v94, s[4:5]
	v_cndmask_b32_e64 v85, v85, v97, s[4:5]
	v_cndmask_b32_e64 v84, v84, v96, s[4:5]
	s_and_b64 vcc, exec, s[8:9]
	s_mov_b64 s[12:13], -1
	v_cvt_pk_bf16_f32 v80, v84, v85
	v_cvt_pk_bf16_f32 v81, v86, v87
	v_cvt_pk_bf16_f32 v82, v88, v89
	v_cvt_pk_bf16_f32 v83, v90, v91
	s_cbranch_vccnz .LBB0_536
	s_and_b64 vcc, exec, s[6:7]
	s_cbranch_vccnz .LBB0_533
	s_andn2_b64 vcc, exec, s[2:3]
	s_cbranch_vccnz .LBB0_530
	s_mov_b64 s[12:13], s[94:95]
	s_mov_b64 s[14:15], s[96:97]
	v_cndmask_b32_e64 v94, v108, v110, s[10:11]
	v_mov_b32_e32 v95, s81
	v_mov_b32_e32 v96, s82
	v_cndmask_b32_e64 v136, v95, v96, s[10:11]
	v_ashrrev_i32_e32 v95, 31, v94
	s_waitcnt lgkmcnt(0)
	v_lshl_add_u64 v[96:97], s[14:15], 0, v[136:137]
	v_lshlrev_b64 v[94:95], 10, v[94:95]
	s_ashr_i32 s57, s56, 31
	v_lshl_add_u64 v[94:95], v[96:97], 0, v[94:95]
	v_lshl_add_u64 v[96:97], v[150:151], 0, s[56:57]
	v_lshl_add_u64 v[94:95], v[96:97], 1, v[94:95]
	v_lshlrev_b32_e32 v136, 2, v111
	global_store_dwordx4 v[94:95], v[80:83], off offset:256
	v_lshl_add_u64 v[94:95], s[12:13], 0, v[136:137]
	v_lshl_add_u64 v[94:95], v[94:95], 0, v[106:107]
	v_lshl_add_u64 v[94:95], v[96:97], 2, v[94:95]
	s_mov_b64 s[12:13], 0
	global_store_dwordx4 v[94:95], v[84:87], off offset:512
	global_store_dwordx4 v[94:95], v[88:91], off offset:528
.LBB0_530:
	s_andn2_b64 vcc, exec, s[12:13]
	s_cbranch_vccnz .LBB0_532
	s_mov_b64 s[12:13], s[94:95]
	s_mov_b64 s[14:15], s[96:97]
	v_mov_b32_e32 v136, v150
	s_waitcnt lgkmcnt(0)
	v_lshl_add_u64 v[84:85], s[14:15], 0, v[104:105]
	v_lshl_add_u64 v[84:85], v[136:137], 1, v[84:85]
	v_add_co_u32_e32 v84, vcc, 0xd0ff000, v84
	s_nop 1
	v_addc_co_u32_e32 v85, vcc, 0, v85, vcc
	global_store_dwordx4 v[84:85], v[80:83], off offset:1280

; __device__ __forceinline__ void route_in(unsigned char* ws, float* out, float qscale, int row, int c, f32x4 v0, f32x4 v1) {
;     ...
;     else if (pn < 6) { const int cc = c - 512; *(u32x4*)((bf16_t*)(ws + WS_XBC) + (size_t)row * 1024 + cc) = w;
.LBB0_533:
	s_andn2_b64 vcc, exec, s[12:13]
	s_cbranch_vccnz .LBB0_535
	s_mov_b64 s[12:13], s[94:95]
	s_mov_b64 s[14:15], s[96:97]
	v_mov_b32_e32 v136, v150
	s_waitcnt lgkmcnt(0)
	v_lshl_add_u64 v[84:85], s[14:15], 0, v[102:103]
	v_lshl_add_u64 v[84:85], v[136:137], 1, v[84:85]
	v_add_co_u32_e32 v84, vcc, 0x6eff000, v84
	s_nop 1
	v_addc_co_u32_e32 v85, vcc, 0, v85, vcc
	global_store_dwordx4 v[84:85], v[80:83], off offset:3328

; __device__ __forceinline__ unsigned cvt_pk_bf16(float lo, float hi) { unsigned r; asm volatile("v_cvt_pk_bf16_f32 %0, %1, %2" : "=v"(r) : "v"(lo), "v"(hi)); return r; }
; __device__ __forceinline__ void route_in(unsigned char* ws, float* out, float qscale, int row, int c, f32x4 v0, f32x4 v1) {
;     const int pn = c >> 8; const bool smp = row >= MPc; const int sb = (row - MPc) >> 6, ts = row & 63;
;     if (pn >= 6 && pn < 8) { v0 = v0 * qscale; v1 = v1 * qscale; }
;     u32x4 w; w.x = cvt_pk_bf16(v0[0], v0[1]); w.y = cvt_pk_bf16(v0[2], v0[3]); w.z = cvt_pk_bf16(v1[0], v1[1]); w.w = cvt_pk_bf16(v1[2], v1[3]);
;     if (pn < 2) { *(u32x4*)((bf16_t*)(ws + WS_Z) + (size_t)row * 512 + c) = w; }
;     else if (pn < 6) { const int cc = c - 512; *(u32x4*)((bf16_t*)(ws + WS_XBC) + (size_t)row * 1024 + cc) = w;
;         if (!smp) { const int tt = row & 4095; if (tt >= 4093) { float* p = out + O_CONVP + (size_t)((row >> 12) * 3 + tt - 4093) * 1024 + cc; *(f32x4*)p = v0; *(f32x4*)(p + 4) = v1; } }
;         else if (ts >= 61) { float* p = out + O_CONVS + (size_t)(sb * 3 + ts - 61) * 1024 + cc; *(f32x4*)p = v0; *(f32x4*)(p + 4) = v1; } }
;     else if (pn < 8) { const int cc = c - 1536; const size_t qrow = smp ? (size_t)(MPc + sb * 256 + ts) : (size_t)row; *(u32x4*)((bf16_t*)(ws + WS_Q) + qrow * 512 + cc) = w; }
;     else { const bool isk = pn < 10; const int cc = c - (isk ? 2048 : 2560);
;         bf16_t* bp = smp ? (bf16_t*)(ws + (isk ? WS_KS : WS_VS)) + (size_t)(sb * 2176 + 2048 + ts) * 512 + cc : (bf16_t*)(ws + (isk ? WS_K : WS_V)) + (size_t)row * 512 + cc;
;         *(u32x4*)bp = w;
;         float* fp = smp ? out + (isk ? O_NKS : O_NVS) + (size_t)(row - MPc) * 512 + cc : out + (isk ? O_NKP : O_NVP) + (size_t)row * 512 + cc;
;         *(f32x4*)fp = v0; *(f32x4*)(fp + 4) = v1; }
;     __device__ __forceinline__ void operator()(const f32x4 (&acc)[2][2][4][2], const Unit& u, int wr, int wc, int fr, int fq) const {
;     ...
;         for (int ai = 0; ai < 2; ++ai)
; #pragma unroll
;             for (int m = 0; m < 4; ++m) { const int row = u.pm * BM + ai * HALF + wr * 64 + m * 16 + fr;
; #pragma unroll
;                 for (int bj = 0; bj < 2; ++bj) route_in(ws, out, qscale, row, colt + bj * HALF, acc[ai][bj][m][0], acc[ai][bj][m][1]); }
.LBB0_538:
	s_nop 1
	v_ashrrev_i32_e32 v80, 12, v145
	v_or_b32_e32 v85, 48, v143
	v_mul_lo_u32 v80, v80, 3
	v_or_b32_e32 v98, v85, v145
	v_add_u32_e32 v82, 0xfffff003, v80
	v_add_u32_e32 v80, 0xffff8000, v98
	v_ashrrev_i32_e32 v99, 31, v98
	v_cmp_lt_i32_e64 s[16:17], s77, v98
	v_ashrrev_i32_e32 v83, 6, v80
	v_or_b32_e32 v87, 0x8030, v143
	v_cndmask_b32_e64 v81, v99, 0, s[16:17]
	v_cndmask_b32_e64 v80, v98, v80, s[16:17]
	v_lshlrev_b64 v[96:97], 11, v[80:81]
	v_lshl_add_u32 v80, v83, 8, v87
	v_cndmask_b32_e64 v80, v98, v80, s[16:17]
	v_ashrrev_i32_e32 v81, 31, v80
	v_or_b32_e32 v84, 0x830, v143
	v_lshlrev_b64 v[94:95], 10, v[80:81]
	v_bitop3_b32 v80, v85, s79, v145 bitop3:0xc8
	v_mad_u64_u32 v[102:103], s[10:11], v83, s78, v[84:85]
	v_mov_b32_e32 v86, s83
	v_mov_b32_e32 v88, s84
	v_cmp_lt_u32_e64 s[14:15], s80, v80
	v_add_u32_e32 v80, v82, v80
	v_cndmask_b32_e64 v103, v86, v88, s[16:17]
	v_ashrrev_i32_e32 v81, 31, v80
	v_add_u32_e32 v86, -13, v143
	v_lshlrev_b64 v[90:91], 12, v[80:81]
	v_mad_u64_u32 v[80:81], s[58:59], v83, 3, v[86:87]
	v_ashrrev_i32_e32 v81, 31, v80
	v_lshlrev_b64 v[88:89], 12, v[80:81]
	v_pk_mul_f32 v[104:105], v[78:79], s[54:55] op_sel_hi:[1,0]
	v_pk_mul_f32 v[106:107], v[76:77], s[54:55] op_sel_hi:[1,0]
	v_pk_mul_f32 v[80:81], v[74:75], s[54:55] op_sel_hi:[1,0]
	v_pk_mul_f32 v[108:109], v[72:73], s[54:55] op_sel_hi:[1,0]
	v_cmp_gt_i32_e64 s[12:13], s72, v98
	v_lshlrev_b64 v[92:93], 11, v[98:99]
	v_cmp_lt_u32_e64 s[10:11], 60, v85
	v_cndmask_b32_e64 v83, v75, v81, s[4:5]
	v_cndmask_b32_e64 v82, v74, v80, s[4:5]
	v_cndmask_b32_e64 v81, v73, v109, s[4:5]
	v_cndmask_b32_e64 v80, v72, v108, s[4:5]
	v_cndmask_b32_e64 v79, v79, v105, s[4:5]
	v_cndmask_b32_e64 v78, v78, v104, s[4:5]
	v_cndmask_b32_e64 v77, v77, v107, s[4:5]
	v_cndmask_b32_e64 v76, v76, v106, s[4:5]
	s_and_b64 vcc, exec, s[8:9]
	s_mov_b64 s[58:59], -1
	v_cvt_pk_bf16_f32 v72, v76, v77
	v_cvt_pk_bf16_f32 v73, v78, v79
	v_cvt_pk_bf16_f32 v74, v80, v81
	v_cvt_pk_bf16_f32 v75, v82, v83
	s_cbranch_vccnz .LBB0_556
	s_and_b64 vcc, exec, s[6:7]
	s_cbranch_vccnz .LBB0_545
	s_andn2_b64 vcc, exec, s[2:3]
	s_cbranch_vccnz .LBB0_542
	v_readlane_b32 s58, v254, 11
	v_readlane_b32 s59, v254, 12
	s_mov_b64 s[88:89], s[94:95]
	s_mov_b64 s[90:91], s[96:97]
	v_cndmask_b32_e64 v106, v98, v102, s[16:17]
	v_mov_b32_e32 v105, s81
	v_mov_b32_e32 v107, s82
	v_cndmask_b32_e64 v136, v105, v107, s[16:17]
	v_ashrrev_i32_e32 v107, 31, v106
	v_add_u32_e32 v104, s56, v150
	s_waitcnt lgkmcnt(0)
	v_lshl_add_u64 v[108:109], s[90:91], 0, v[136:137]
	v_lshlrev_b64 v[106:107], 10, v[106:107]
	v_lshl_add_u64 v[106:107], v[108:109], 0, v[106:107]
	v_ashrrev_i32_e32 v105, 31, v104
	v_lshl_add_u64 v[106:107], v[104:105], 1, v[106:107]
	v_lshlrev_b32_e32 v136, 2, v103
	global_store_dwordx4 v[106:107], v[72:75], off
	v_lshl_add_u64 v[106:107], s[88:89], 0, v[136:137]
	v_lshl_add_u64 v[106:107], v[106:107], 0, v[96:97]
	v_lshl_add_u64 v[104:105], v[104:105], 2, v[106:107]
	s_mov_b64 s[58:59], 0
	global_store_dwordx4 v[104:105], v[76:79], off
	global_store_dwordx4 v[104:105], v[80:83], off offset:16
.LBB0_542:
	s_andn2_b64 vcc, exec, s[58:59]
	s_cbranch_vccnz .LBB0_544
	v_readlane_b32 s58, v254, 11
	v_readlane_b32 s59, v254, 12
	s_mov_b64 s[88:89], s[94:95]
	s_mov_b64 s[90:91], s[96:97]
	v_mov_b32_e32 v136, v150
	s_waitcnt lgkmcnt(0)
	v_lshl_add_u64 v[104:105], s[90:91], 0, v[94:95]
	v_lshl_add_u64 v[104:105], v[136:137], 1, v[104:105]
	v_add_co_u32_e32 v104, vcc, 0xd0ff000, v104
	s_nop 1
	v_addc_co_u32_e32 v105, vcc, 0, v105, vcc
	global_store_dwordx4 v[104:105], v[72:75], off offset:1024

; __device__ __forceinline__ unsigned cvt_pk_bf16(float lo, float hi) { unsigned r; asm volatile("v_cvt_pk_bf16_f32 %0, %1, %2" : "=v"(r) : "v"(lo), "v"(hi)); return r; }
; __device__ __forceinline__ void route_in(unsigned char* ws, float* out, float qscale, int row, int c, f32x4 v0, f32x4 v1) {
;     const int pn = c >> 8; const bool smp = row >= MPc; const int sb = (row - MPc) >> 6, ts = row & 63;
;     if (pn >= 6 && pn < 8) { v0 = v0 * qscale; v1 = v1 * qscale; }
;     u32x4 w; w.x = cvt_pk_bf16(v0[0], v0[1]); w.y = cvt_pk_bf16(v0[2], v0[3]); w.z = cvt_pk_bf16(v1[0], v1[1]); w.w = cvt_pk_bf16(v1[2], v1[3]);
;     if (pn < 2) { *(u32x4*)((bf16_t*)(ws + WS_Z) + (size_t)row * 512 + c) = w; }
;     else if (pn < 6) { const int cc = c - 512; *(u32x4*)((bf16_t*)(ws + WS_XBC) + (size_t)row * 1024 + cc) = w;
;         if (!smp) { const int tt = row & 4095; if (tt >= 4093) { float* p = out + O_CONVP + (size_t)((row >> 12) * 3 + tt - 4093) * 1024 + cc; *(f32x4*)p = v0; *(f32x4*)(p + 4) = v1; } }
;         else if (ts >= 61) { float* p = out + O_CONVS + (size_t)(sb * 3 + ts - 61) * 1024 + cc; *(f32x4*)p = v0; *(f32x4*)(p + 4) = v1; } }
;     else if (pn < 8) { const int cc = c - 1536; const size_t qrow = smp ? (size_t)(MPc + sb * 256 + ts) : (size_t)row; *(u32x4*)((bf16_t*)(ws + WS_Q) + qrow * 512 + cc) = w; }
;     else { const bool isk = pn < 10; const int cc = c - (isk ? 2048 : 2560);
;         bf16_t* bp = smp ? (bf16_t*)(ws + (isk ? WS_KS : WS_VS)) + (size_t)(sb * 2176 + 2048 + ts) * 512 + cc : (bf16_t*)(ws + (isk ? WS_K : WS_V)) + (size_t)row * 512 + cc;
;         *(u32x4*)bp = w;
;         float* fp = smp ? out + (isk ? O_NKS : O_NVS) + (size_t)(row - MPc) * 512 + cc : out + (isk ? O_NKP : O_NVP) + (size_t)row * 512 + cc;
;         *(f32x4*)fp = v0; *(f32x4*)(fp + 4) = v1; }
;     __device__ __forceinline__ void operator()(const f32x4 (&acc)[2][2][4][2], const Unit& u, int wr, int wc, int fr, int fq) const {
;     ...
;                 for (int bj = 0; bj < 2; ++bj) route_in(ws, out, qscale, row, colt + bj * HALF, acc[ai][bj][m][0], acc[ai][bj][m][1]); }
.LBB0_558:
	v_pk_mul_f32 v[78:79], v[70:71], s[54:55] op_sel_hi:[1,0]
	v_pk_mul_f32 v[80:81], v[68:69], s[54:55] op_sel_hi:[1,0]
	v_pk_mul_f32 v[72:73], v[66:67], s[54:55] op_sel_hi:[1,0]
	v_pk_mul_f32 v[82:83], v[64:65], s[54:55] op_sel_hi:[1,0]
	v_cndmask_b32_e64 v75, v67, v73, s[4:5]
	v_cndmask_b32_e64 v74, v66, v72, s[4:5]
	v_cndmask_b32_e64 v73, v65, v83, s[4:5]
	v_cndmask_b32_e64 v72, v64, v82, s[4:5]
	v_cndmask_b32_e64 v71, v71, v79, s[4:5]
	v_cndmask_b32_e64 v70, v70, v78, s[4:5]
	v_cndmask_b32_e64 v69, v69, v81, s[4:5]
	v_cndmask_b32_e64 v68, v68, v80, s[4:5]
	s_and_b64 vcc, exec, s[8:9]
	s_mov_b64 s[58:59], -1
	v_cvt_pk_bf16_f32 v64, v68, v69
	v_cvt_pk_bf16_f32 v65, v70, v71
	v_cvt_pk_bf16_f32 v66, v72, v73
	v_cvt_pk_bf16_f32 v67, v74, v75
	s_cbranch_vccnz .LBB0_576
	s_and_b64 vcc, exec, s[6:7]
	s_cbranch_vccnz .LBB0_565
	s_andn2_b64 vcc, exec, s[2:3]
	s_cbranch_vccnz .LBB0_562
	v_mov_b32_e32 v79, s81
	v_mov_b32_e32 v80, s82
	v_cndmask_b32_e64 v78, v98, v102, s[16:17]
	v_cndmask_b32_e64 v136, v79, v80, s[16:17]
	v_readlane_b32 s16, v254, 11
	v_readlane_b32 s17, v254, 12
	s_mov_b64 s[88:89], s[94:95]
	s_mov_b64 s[90:91], s[96:97]
	v_ashrrev_i32_e32 v79, 31, v78
	v_lshlrev_b64 v[78:79], 10, v[78:79]
	s_ashr_i32 s57, s56, 31
	s_mov_b64 s[58:59], 0
	s_waitcnt lgkmcnt(0)
	v_lshl_add_u64 v[80:81], s[90:91], 0, v[136:137]
	v_lshl_add_u64 v[78:79], v[80:81], 0, v[78:79]
	v_lshl_add_u64 v[80:81], v[150:151], 0, s[56:57]
	v_lshl_add_u64 v[78:79], v[80:81], 1, v[78:79]
	v_lshlrev_b32_e32 v136, 2, v103
	global_store_dwordx4 v[78:79], v[64:67], off offset:256
	v_lshl_add_u64 v[78:79], s[88:89], 0, v[136:137]
	v_lshl_add_u64 v[78:79], v[78:79], 0, v[96:97]
	v_lshl_add_u64 v[78:79], v[80:81], 2, v[78:79]
	global_store_dwordx4 v[78:79], v[68:71], off offset:512
	global_store_dwordx4 v[78:79], v[72:75], off offset:528
.LBB0_562:
	s_andn2_b64 vcc, exec, s[58:59]
	s_cbranch_vccnz .LBB0_564
	v_readlane_b32 s16, v254, 11
	v_readlane_b32 s17, v254, 12
	s_mov_b64 s[88:89], s[94:95]
	s_mov_b64 s[90:91], s[96:97]
	v_mov_b32_e32 v136, v150
	s_waitcnt lgkmcnt(0)
	v_lshl_add_u64 v[78:79], s[90:91], 0, v[94:95]
	v_lshl_add_u64 v[78:79], v[136:137], 1, v[78:79]
	v_add_co_u32_e32 v78, vcc, 0xd0ff000, v78
	s_nop 1
	v_addc_co_u32_e32 v79, vcc, 0, v79, vcc
	global_store_dwordx4 v[78:79], v[64:67], off offset:1280

; __device__ __forceinline__ unsigned cvt_pk_bf16(float lo, float hi) { unsigned r; asm volatile("v_cvt_pk_bf16_f32 %0, %1, %2" : "=v"(r) : "v"(lo), "v"(hi)); return r; }
; __device__ __forceinline__ void route_in(unsigned char* ws, float* out, float qscale, int row, int c, f32x4 v0, f32x4 v1) {
;     const int pn = c >> 8; const bool smp = row >= MPc; const int sb = (row - MPc) >> 6, ts = row & 63;
;     if (pn >= 6 && pn < 8) { v0 = v0 * qscale; v1 = v1 * qscale; }
;     u32x4 w; w.x = cvt_pk_bf16(v0[0], v0[1]); w.y = cvt_pk_bf16(v0[2], v0[3]); w.z = cvt_pk_bf16(v1[0], v1[1]); w.w = cvt_pk_bf16(v1[2], v1[3]);
;     if (pn < 2) { *(u32x4*)((bf16_t*)(ws + WS_Z) + (size_t)row * 512 + c) = w; }
;     else if (pn < 6) { const int cc = c - 512; *(u32x4*)((bf16_t*)(ws + WS_XBC) + (size_t)row * 1024 + cc) = w;
;         if (!smp) { const int tt = row & 4095; if (tt >= 4093) { float* p = out + O_CONVP + (size_t)((row >> 12) * 3 + tt - 4093) * 1024 + cc; *(f32x4*)p = v0; *(f32x4*)(p + 4) = v1; } }
;         else if (ts >= 61) { float* p = out + O_CONVS + (size_t)(sb * 3 + ts - 61) * 1024 + cc; *(f32x4*)p = v0; *(f32x4*)(p + 4) = v1; } }
;     else if (pn < 8) { const int cc = c - 1536; const size_t qrow = smp ? (size_t)(MPc + sb * 256 + ts) : (size_t)row; *(u32x4*)((bf16_t*)(ws + WS_Q) + qrow * 512 + cc) = w; }
;     else { const bool isk = pn < 10; const int cc = c - (isk ? 2048 : 2560);
;         bf16_t* bp = smp ? (bf16_t*)(ws + (isk ? WS_KS : WS_VS)) + (size_t)(sb * 2176 + 2048 + ts) * 512 + cc : (bf16_t*)(ws + (isk ? WS_K : WS_V)) + (size_t)row * 512 + cc;
;         *(u32x4*)bp = w;
;         float* fp = smp ? out + (isk ? O_NKS : O_NVS) + (size_t)(row - MPc) * 512 + cc : out + (isk ? O_NKP : O_NVP) + (size_t)row * 512 + cc;
;         *(f32x4*)fp = v0; *(f32x4*)(fp + 4) = v1; }
;     __device__ __forceinline__ void operator()(const f32x4 (&acc)[2][2][4][2], const Unit& u, int wr, int wc, int fr, int fq) const {
;     ...
;         for (int ai = 0; ai < 2; ++ai)
; #pragma unroll
;             for (int m = 0; m < 4; ++m) { const int row = u.pm * BM + ai * HALF + wr * 64 + m * 16 + fr;
; #pragma unroll
;                 for (int bj = 0; bj < 2; ++bj) route_in(ws, out, qscale, row, colt + bj * HALF, acc[ai][bj][m][0], acc[ai][bj][m][1]); }
.LBB0_578:
	v_add_u32_e32 v78, 0x80, v145
	v_or_b32_e32 v74, v143, v78
	v_add_u32_e32 v64, 0xffff8000, v74
	v_ashrrev_i32_e32 v66, 6, v64
	v_mad_u64_u32 v[76:77], s[12:13], v66, s78, v[152:153]
	v_ashrrev_i32_e32 v75, 31, v74
	v_cmp_lt_i32_e64 s[12:13], s77, v74
	v_mov_b32_e32 v67, s83
	v_mov_b32_e32 v68, s84
	v_cndmask_b32_e64 v65, v75, 0, s[12:13]
	v_cndmask_b32_e64 v64, v74, v64, s[12:13]
	v_lshlrev_b64 v[72:73], 11, v[64:65]
	v_lshl_add_u32 v64, v66, 8, v153
	v_cndmask_b32_e64 v64, v74, v64, s[12:13]
	v_ashrrev_i32_e32 v65, 31, v64
	v_lshlrev_b64 v[70:71], 10, v[64:65]
	v_pk_mul_f32 v[80:81], v[62:63], s[54:55] op_sel_hi:[1,0]
	v_pk_mul_f32 v[82:83], v[60:61], s[54:55] op_sel_hi:[1,0]
	v_pk_mul_f32 v[64:65], v[58:59], s[54:55] op_sel_hi:[1,0]
	v_pk_mul_f32 v[88:89], v[56:57], s[54:55] op_sel_hi:[1,0]
	v_readlane_b32 s16, v254, 11
	v_cndmask_b32_e64 v77, v67, v68, s[12:13]
	v_lshlrev_b64 v[68:69], 11, v[74:75]
	v_cndmask_b32_e64 v67, v59, v65, s[4:5]
	v_cndmask_b32_e64 v66, v58, v64, s[4:5]
	v_cndmask_b32_e64 v65, v57, v89, s[4:5]
	v_cndmask_b32_e64 v64, v56, v88, s[4:5]
	v_cndmask_b32_e64 v63, v63, v81, s[4:5]
	v_cndmask_b32_e64 v62, v62, v80, s[4:5]
	v_cndmask_b32_e64 v61, v61, v83, s[4:5]
	v_cndmask_b32_e64 v60, v60, v82, s[4:5]
	s_and_b64 vcc, exec, s[8:9]
	s_mov_b64 s[14:15], -1
	v_readlane_b32 s17, v254, 12
	v_cvt_pk_bf16_f32 v56, v60, v61
	v_cvt_pk_bf16_f32 v57, v62, v63
	v_cvt_pk_bf16_f32 v58, v64, v65
	v_cvt_pk_bf16_f32 v59, v66, v67
	s_cbranch_vccnz .LBB0_588
	s_and_b64 vcc, exec, s[6:7]
	s_cbranch_vccnz .LBB0_585
	s_andn2_b64 vcc, exec, s[2:3]
	s_cbranch_vccnz .LBB0_582
	s_mov_b64 s[88:89], s[94:95]
	s_mov_b64 s[90:91], s[96:97]
	v_cndmask_b32_e64 v82, v74, v76, s[12:13]
	v_mov_b32_e32 v79, s81
	v_mov_b32_e32 v81, s82
	v_cndmask_b32_e64 v136, v79, v81, s[12:13]
	v_ashrrev_i32_e32 v83, 31, v82
	v_add_u32_e32 v80, s56, v150
	s_waitcnt lgkmcnt(0)
	v_lshl_add_u64 v[88:89], s[90:91], 0, v[136:137]
	v_lshlrev_b64 v[82:83], 10, v[82:83]
	v_lshl_add_u64 v[82:83], v[88:89], 0, v[82:83]
	v_ashrrev_i32_e32 v81, 31, v80
	v_lshl_add_u64 v[82:83], v[80:81], 1, v[82:83]
	v_lshlrev_b32_e32 v136, 2, v77
	global_store_dwordx4 v[82:83], v[56:59], off
	v_lshl_add_u64 v[82:83], s[88:89], 0, v[136:137]
	v_lshl_add_u64 v[82:83], v[82:83], 0, v[72:73]
	v_lshl_add_u64 v[80:81], v[80:81], 2, v[82:83]
	s_mov_b64 s[14:15], 0
	global_store_dwordx4 v[80:81], v[60:63], off
	global_store_dwordx4 v[80:81], v[64:67], off offset:16
.LBB0_582:
	s_andn2_b64 vcc, exec, s[14:15]
	s_cbranch_vccnz .LBB0_584
	s_mov_b64 s[88:89], s[94:95]
	s_mov_b64 s[90:91], s[96:97]
	v_mov_b32_e32 v136, v150
	s_waitcnt lgkmcnt(0)
	v_lshl_add_u64 v[60:61], s[90:91], 0, v[70:71]
	v_lshl_add_u64 v[60:61], v[136:137], 1, v[60:61]
	v_add_co_u32_e32 v60, vcc, 0xd0ff000, v60
	s_nop 1
	v_addc_co_u32_e32 v61, vcc, 0, v61, vcc
	global_store_dwordx4 v[60:61], v[56:59], off offset:1024

; __device__ __forceinline__ void route_in(unsigned char* ws, float* out, float qscale, int row, int c, f32x4 v0, f32x4 v1) {
;     ...
;     else if (pn < 6) { const int cc = c - 512; *(u32x4*)((bf16_t*)(ws + WS_XBC) + (size_t)row * 1024 + cc) = w;
.LBB0_585:
	s_andn2_b64 vcc, exec, s[14:15]
	s_cbranch_vccnz .LBB0_587
	s_mov_b64 s[88:89], s[94:95]
	s_mov_b64 s[90:91], s[96:97]
	v_mov_b32_e32 v136, v150
	s_waitcnt lgkmcnt(0)
	v_lshl_add_u64 v[60:61], s[90:91], 0, v[68:69]
	v_lshl_add_u64 v[60:61], v[136:137], 1, v[60:61]
	v_add_co_u32_e32 v60, vcc, 0x6eff000, v60
	s_nop 1
	v_addc_co_u32_e32 v61, vcc, 0, v61, vcc
	global_store_dwordx4 v[60:61], v[56:59], off offset:3072

; __device__ __forceinline__ unsigned cvt_pk_bf16(float lo, float hi) { unsigned r; asm volatile("v_cvt_pk_bf16_f32 %0, %1, %2" : "=v"(r) : "v"(lo), "v"(hi)); return r; }
; __device__ __forceinline__ void route_in(unsigned char* ws, float* out, float qscale, int row, int c, f32x4 v0, f32x4 v1) {
;     const int pn = c >> 8; const bool smp = row >= MPc; const int sb = (row - MPc) >> 6, ts = row & 63;
;     if (pn >= 6 && pn < 8) { v0 = v0 * qscale; v1 = v1 * qscale; }
;     u32x4 w; w.x = cvt_pk_bf16(v0[0], v0[1]); w.y = cvt_pk_bf16(v0[2], v0[3]); w.z = cvt_pk_bf16(v1[0], v1[1]); w.w = cvt_pk_bf16(v1[2], v1[3]);
;     if (pn < 2) { *(u32x4*)((bf16_t*)(ws + WS_Z) + (size_t)row * 512 + c) = w; }
;     else if (pn < 6) { const int cc = c - 512; *(u32x4*)((bf16_t*)(ws + WS_XBC) + (size_t)row * 1024 + cc) = w;
;         if (!smp) { const int tt = row & 4095; if (tt >= 4093) { float* p = out + O_CONVP + (size_t)((row >> 12) * 3 + tt - 4093) * 1024 + cc; *(f32x4*)p = v0; *(f32x4*)(p + 4) = v1; } }
;         else if (ts >= 61) { float* p = out + O_CONVS + (size_t)(sb * 3 + ts - 61) * 1024 + cc; *(f32x4*)p = v0; *(f32x4*)(p + 4) = v1; } }
;     else if (pn < 8) { const int cc = c - 1536; const size_t qrow = smp ? (size_t)(MPc + sb * 256 + ts) : (size_t)row; *(u32x4*)((bf16_t*)(ws + WS_Q) + qrow * 512 + cc) = w; }
;     else { const bool isk = pn < 10; const int cc = c - (isk ? 2048 : 2560);
;         bf16_t* bp = smp ? (bf16_t*)(ws + (isk ? WS_KS : WS_VS)) + (size_t)(sb * 2176 + 2048 + ts) * 512 + cc : (bf16_t*)(ws + (isk ? WS_K : WS_V)) + (size_t)row * 512 + cc;
;         *(u32x4*)bp = w;
;         float* fp = smp ? out + (isk ? O_NKS : O_NVS) + (size_t)(row - MPc) * 512 + cc : out + (isk ? O_NKP : O_NVP) + (size_t)row * 512 + cc;
;         *(f32x4*)fp = v0; *(f32x4*)(fp + 4) = v1; }
;     __device__ __forceinline__ void operator()(const f32x4 (&acc)[2][2][4][2], const Unit& u, int wr, int wc, int fr, int fq) const {
;     ...
;                 for (int bj = 0; bj < 2; ++bj) route_in(ws, out, qscale, row, colt + bj * HALF, acc[ai][bj][m][0], acc[ai][bj][m][1]); }
.LBB0_590:
	v_pk_mul_f32 v[62:63], v[54:55], s[54:55] op_sel_hi:[1,0]
	v_pk_mul_f32 v[64:65], v[52:53], s[54:55] op_sel_hi:[1,0]
	v_pk_mul_f32 v[56:57], v[50:51], s[54:55] op_sel_hi:[1,0]
	v_pk_mul_f32 v[66:67], v[48:49], s[54:55] op_sel_hi:[1,0]
	v_cndmask_b32_e64 v59, v51, v57, s[4:5]
	v_cndmask_b32_e64 v58, v50, v56, s[4:5]
	v_cndmask_b32_e64 v57, v49, v67, s[4:5]
	v_cndmask_b32_e64 v56, v48, v66, s[4:5]
	v_cndmask_b32_e64 v55, v55, v63, s[4:5]
	v_cndmask_b32_e64 v54, v54, v62, s[4:5]
	v_cndmask_b32_e64 v53, v53, v65, s[4:5]
	v_cndmask_b32_e64 v52, v52, v64, s[4:5]
	s_and_b64 vcc, exec, s[8:9]
	s_mov_b64 s[14:15], -1
	v_cvt_pk_bf16_f32 v48, v52, v53
	v_cvt_pk_bf16_f32 v49, v54, v55
	v_cvt_pk_bf16_f32 v50, v56, v57
	v_cvt_pk_bf16_f32 v51, v58, v59
	s_cbranch_vccnz .LBB0_600
	s_and_b64 vcc, exec, s[6:7]
	s_cbranch_vccnz .LBB0_597
	s_andn2_b64 vcc, exec, s[2:3]
	s_cbranch_vccnz .LBB0_594
	v_mov_b32_e32 v63, s81
	v_mov_b32_e32 v64, s82
	v_cndmask_b32_e64 v62, v74, v76, s[12:13]
	v_cndmask_b32_e64 v136, v63, v64, s[12:13]
	s_mov_b64 s[12:13], s[94:95]
	s_mov_b64 s[14:15], s[96:97]
	v_ashrrev_i32_e32 v63, 31, v62
	v_lshlrev_b64 v[62:63], 10, v[62:63]
	s_ashr_i32 s57, s56, 31
	s_waitcnt lgkmcnt(0)
	v_lshl_add_u64 v[64:65], s[14:15], 0, v[136:137]
	v_lshl_add_u64 v[62:63], v[64:65], 0, v[62:63]
	v_lshl_add_u64 v[64:65], v[150:151], 0, s[56:57]
	v_lshl_add_u64 v[62:63], v[64:65], 1, v[62:63]
	v_lshlrev_b32_e32 v136, 2, v77
	global_store_dwordx4 v[62:63], v[48:51], off offset:256
	v_lshl_add_u64 v[62:63], s[12:13], 0, v[136:137]
	v_lshl_add_u64 v[62:63], v[62:63], 0, v[72:73]
	v_lshl_add_u64 v[62:63], v[64:65], 2, v[62:63]
	s_mov_b64 s[14:15], 0
	global_store_dwordx4 v[62:63], v[52:55], off offset:512
	global_store_dwordx4 v[62:63], v[56:59], off offset:528
.LBB0_594:
	s_andn2_b64 vcc, exec, s[14:15]
	s_cbranch_vccnz .LBB0_596
	s_mov_b64 s[12:13], s[94:95]
	s_mov_b64 s[14:15], s[96:97]
	v_mov_b32_e32 v136, v150
	s_waitcnt lgkmcnt(0)
	v_lshl_add_u64 v[52:53], s[14:15], 0, v[70:71]
	v_lshl_add_u64 v[52:53], v[136:137], 1, v[52:53]
	v_add_co_u32_e32 v52, vcc, 0xd0ff000, v52
	s_nop 1
	v_addc_co_u32_e32 v53, vcc, 0, v53, vcc
	global_store_dwordx4 v[52:53], v[48:51], off offset:1280

; __device__ __forceinline__ void route_in(unsigned char* ws, float* out, float qscale, int row, int c, f32x4 v0, f32x4 v1) {
;     ...
;     else if (pn < 6) { const int cc = c - 512; *(u32x4*)((bf16_t*)(ws + WS_XBC) + (size_t)row * 1024 + cc) = w;
.LBB0_597:
	s_andn2_b64 vcc, exec, s[14:15]
	s_cbranch_vccnz .LBB0_599
	s_mov_b64 s[12:13], s[94:95]
	s_mov_b64 s[14:15], s[96:97]
	v_mov_b32_e32 v136, v150
	s_waitcnt lgkmcnt(0)
	v_lshl_add_u64 v[52:53], s[14:15], 0, v[68:69]
	v_lshl_add_u64 v[52:53], v[136:137], 1, v[52:53]
	v_add_co_u32_e32 v52, vcc, 0x6eff000, v52
	s_nop 1
	v_addc_co_u32_e32 v53, vcc, 0, v53, vcc
	global_store_dwordx4 v[52:53], v[48:51], off offset:3328

; __device__ __forceinline__ unsigned cvt_pk_bf16(float lo, float hi) { unsigned r; asm volatile("v_cvt_pk_bf16_f32 %0, %1, %2" : "=v"(r) : "v"(lo), "v"(hi)); return r; }
; __device__ __forceinline__ void route_in(unsigned char* ws, float* out, float qscale, int row, int c, f32x4 v0, f32x4 v1) {
;     const int pn = c >> 8; const bool smp = row >= MPc; const int sb = (row - MPc) >> 6, ts = row & 63;
;     if (pn >= 6 && pn < 8) { v0 = v0 * qscale; v1 = v1 * qscale; }
;     u32x4 w; w.x = cvt_pk_bf16(v0[0], v0[1]); w.y = cvt_pk_bf16(v0[2], v0[3]); w.z = cvt_pk_bf16(v1[0], v1[1]); w.w = cvt_pk_bf16(v1[2], v1[3]);
;     if (pn < 2) { *(u32x4*)((bf16_t*)(ws + WS_Z) + (size_t)row * 512 + c) = w; }
;     else if (pn < 6) { const int cc = c - 512; *(u32x4*)((bf16_t*)(ws + WS_XBC) + (size_t)row * 1024 + cc) = w;
;         if (!smp) { const int tt = row & 4095; if (tt >= 4093) { float* p = out + O_CONVP + (size_t)((row >> 12) * 3 + tt - 4093) * 1024 + cc; *(f32x4*)p = v0; *(f32x4*)(p + 4) = v1; } }
;         else if (ts >= 61) { float* p = out + O_CONVS + (size_t)(sb * 3 + ts - 61) * 1024 + cc; *(f32x4*)p = v0; *(f32x4*)(p + 4) = v1; } }
;     else if (pn < 8) { const int cc = c - 1536; const size_t qrow = smp ? (size_t)(MPc + sb * 256 + ts) : (size_t)row; *(u32x4*)((bf16_t*)(ws + WS_Q) + qrow * 512 + cc) = w; }
;     else { const bool isk = pn < 10; const int cc = c - (isk ? 2048 : 2560);
;         bf16_t* bp = smp ? (bf16_t*)(ws + (isk ? WS_KS : WS_VS)) + (size_t)(sb * 2176 + 2048 + ts) * 512 + cc : (bf16_t*)(ws + (isk ? WS_K : WS_V)) + (size_t)row * 512 + cc;
;         *(u32x4*)bp = w;
;         float* fp = smp ? out + (isk ? O_NKS : O_NVS) + (size_t)(row - MPc) * 512 + cc : out + (isk ? O_NKP : O_NVP) + (size_t)row * 512 + cc;
;         *(f32x4*)fp = v0; *(f32x4*)(fp + 4) = v1; }
;     __device__ __forceinline__ void operator()(const f32x4 (&acc)[2][2][4][2], const Unit& u, int wr, int wc, int fr, int fq) const {
;     ...
;         for (int ai = 0; ai < 2; ++ai)
; #pragma unroll
;             for (int m = 0; m < 4; ++m) { const int row = u.pm * BM + ai * HALF + wr * 64 + m * 16 + fr;
; #pragma unroll
;                 for (int bj = 0; bj < 2; ++bj) route_in(ws, out, qscale, row, colt + bj * HALF, acc[ai][bj][m][0], acc[ai][bj][m][1]); }
.LBB0_602:
	v_or_b32_e32 v58, v128, v78
	s_nop 0
	v_add_u32_e32 v48, 0xffff8000, v58
	v_ashrrev_i32_e32 v50, 6, v48
	v_mad_u64_u32 v[60:61], s[12:13], v50, s78, v[116:117]
	v_ashrrev_i32_e32 v59, 31, v58
	v_cmp_lt_i32_e64 s[12:13], s77, v58
	v_mov_b32_e32 v51, s83
	v_mov_b32_e32 v52, s84
	v_cndmask_b32_e64 v49, v59, 0, s[12:13]
	v_cndmask_b32_e64 v48, v58, v48, s[12:13]
	v_lshlrev_b64 v[56:57], 11, v[48:49]
	v_lshl_add_u32 v48, v50, 8, v117
	v_cndmask_b32_e64 v48, v58, v48, s[12:13]
	v_ashrrev_i32_e32 v49, 31, v48
	v_lshlrev_b64 v[54:55], 10, v[48:49]
	v_pk_mul_f32 v[62:63], v[46:47], s[54:55] op_sel_hi:[1,0]
	v_pk_mul_f32 v[64:65], v[44:45], s[54:55] op_sel_hi:[1,0]
	v_pk_mul_f32 v[48:49], v[42:43], s[54:55] op_sel_hi:[1,0]
	v_pk_mul_f32 v[66:67], v[40:41], s[54:55] op_sel_hi:[1,0]
	v_cndmask_b32_e64 v61, v51, v52, s[12:13]
	v_lshlrev_b64 v[52:53], 11, v[58:59]
	v_cndmask_b32_e64 v51, v43, v49, s[4:5]
	v_cndmask_b32_e64 v50, v42, v48, s[4:5]
	v_cndmask_b32_e64 v49, v41, v67, s[4:5]
	v_cndmask_b32_e64 v48, v40, v66, s[4:5]
	v_cndmask_b32_e64 v47, v47, v63, s[4:5]
	v_cndmask_b32_e64 v46, v46, v62, s[4:5]
	v_cndmask_b32_e64 v45, v45, v65, s[4:5]
	v_cndmask_b32_e64 v44, v44, v64, s[4:5]
	s_and_b64 vcc, exec, s[8:9]
	s_mov_b64 s[14:15], -1
	v_cvt_pk_bf16_f32 v40, v44, v45
	v_cvt_pk_bf16_f32 v41, v46, v47
	v_cvt_pk_bf16_f32 v42, v48, v49
	v_cvt_pk_bf16_f32 v43, v50, v51
	s_cbranch_vccnz .LBB0_612
	s_and_b64 vcc, exec, s[6:7]
	s_cbranch_vccnz .LBB0_609
	s_andn2_b64 vcc, exec, s[2:3]
	s_cbranch_vccnz .LBB0_606
	s_mov_b64 s[88:89], s[94:95]
	s_mov_b64 s[90:91], s[96:97]
	v_cndmask_b32_e64 v64, v58, v60, s[12:13]
	v_mov_b32_e32 v63, s81
	v_mov_b32_e32 v65, s82
	v_cndmask_b32_e64 v136, v63, v65, s[12:13]
	v_ashrrev_i32_e32 v65, 31, v64
	v_add_u32_e32 v62, s56, v150
	s_waitcnt lgkmcnt(0)
	v_lshl_add_u64 v[66:67], s[90:91], 0, v[136:137]
	v_lshlrev_b64 v[64:65], 10, v[64:65]
	v_lshl_add_u64 v[64:65], v[66:67], 0, v[64:65]
	v_ashrrev_i32_e32 v63, 31, v62
	v_lshl_add_u64 v[64:65], v[62:63], 1, v[64:65]
	v_lshlrev_b32_e32 v136, 2, v61
	global_store_dwordx4 v[64:65], v[40:43], off
	v_lshl_add_u64 v[64:65], s[88:89], 0, v[136:137]
	v_lshl_add_u64 v[64:65], v[64:65], 0, v[56:57]
	v_lshl_add_u64 v[62:63], v[62:63], 2, v[64:65]
	s_mov_b64 s[14:15], 0
	global_store_dwordx4 v[62:63], v[44:47], off
	global_store_dwordx4 v[62:63], v[48:51], off offset:16
.LBB0_606:
	s_andn2_b64 vcc, exec, s[14:15]
	s_cbranch_vccnz .LBB0_608
	s_mov_b64 s[88:89], s[94:95]
	s_mov_b64 s[90:91], s[96:97]
	v_mov_b32_e32 v136, v150
	s_waitcnt lgkmcnt(0)
	v_lshl_add_u64 v[44:45], s[90:91], 0, v[54:55]
	v_lshl_add_u64 v[44:45], v[136:137], 1, v[44:45]
	v_add_co_u32_e32 v44, vcc, 0xd0ff000, v44
	s_nop 1
	v_addc_co_u32_e32 v45, vcc, 0, v45, vcc
	global_store_dwordx4 v[44:45], v[40:43], off offset:1024

; __device__ __forceinline__ void route_in(unsigned char* ws, float* out, float qscale, int row, int c, f32x4 v0, f32x4 v1) {
;     ...
;     else if (pn < 6) { const int cc = c - 512; *(u32x4*)((bf16_t*)(ws + WS_XBC) + (size_t)row * 1024 + cc) = w;
.LBB0_609:
	s_andn2_b64 vcc, exec, s[14:15]
	s_cbranch_vccnz .LBB0_611
	s_mov_b64 s[88:89], s[94:95]
	s_mov_b64 s[90:91], s[96:97]
	v_mov_b32_e32 v136, v150
	s_waitcnt lgkmcnt(0)
	v_lshl_add_u64 v[44:45], s[90:91], 0, v[52:53]
	v_lshl_add_u64 v[44:45], v[136:137], 1, v[44:45]
	v_add_co_u32_e32 v44, vcc, 0x6eff000, v44
	s_nop 1
	v_addc_co_u32_e32 v45, vcc, 0, v45, vcc
	global_store_dwordx4 v[44:45], v[40:43], off offset:3072

; __device__ __forceinline__ unsigned cvt_pk_bf16(float lo, float hi) { unsigned r; asm volatile("v_cvt_pk_bf16_f32 %0, %1, %2" : "=v"(r) : "v"(lo), "v"(hi)); return r; }
; __device__ __forceinline__ void route_in(unsigned char* ws, float* out, float qscale, int row, int c, f32x4 v0, f32x4 v1) {
;     const int pn = c >> 8; const bool smp = row >= MPc; const int sb = (row - MPc) >> 6, ts = row & 63;
;     if (pn >= 6 && pn < 8) { v0 = v0 * qscale; v1 = v1 * qscale; }
;     u32x4 w; w.x = cvt_pk_bf16(v0[0], v0[1]); w.y = cvt_pk_bf16(v0[2], v0[3]); w.z = cvt_pk_bf16(v1[0], v1[1]); w.w = cvt_pk_bf16(v1[2], v1[3]);
;     if (pn < 2) { *(u32x4*)((bf16_t*)(ws + WS_Z) + (size_t)row * 512 + c) = w; }
;     else if (pn < 6) { const int cc = c - 512; *(u32x4*)((bf16_t*)(ws + WS_XBC) + (size_t)row * 1024 + cc) = w;
;         if (!smp) { const int tt = row & 4095; if (tt >= 4093) { float* p = out + O_CONVP + (size_t)((row >> 12) * 3 + tt - 4093) * 1024 + cc; *(f32x4*)p = v0; *(f32x4*)(p + 4) = v1; } }
;         else if (ts >= 61) { float* p = out + O_CONVS + (size_t)(sb * 3 + ts - 61) * 1024 + cc; *(f32x4*)p = v0; *(f32x4*)(p + 4) = v1; } }
;     else if (pn < 8) { const int cc = c - 1536; const size_t qrow = smp ? (size_t)(MPc + sb * 256 + ts) : (size_t)row; *(u32x4*)((bf16_t*)(ws + WS_Q) + qrow * 512 + cc) = w; }
;     else { const bool isk = pn < 10; const int cc = c - (isk ? 2048 : 2560);
;         bf16_t* bp = smp ? (bf16_t*)(ws + (isk ? WS_KS : WS_VS)) + (size_t)(sb * 2176 + 2048 + ts) * 512 + cc : (bf16_t*)(ws + (isk ? WS_K : WS_V)) + (size_t)row * 512 + cc;
;         *(u32x4*)bp = w;
;         float* fp = smp ? out + (isk ? O_NKS : O_NVS) + (size_t)(row - MPc) * 512 + cc : out + (isk ? O_NKP : O_NVP) + (size_t)row * 512 + cc;
;         *(f32x4*)fp = v0; *(f32x4*)(fp + 4) = v1; }
;     __device__ __forceinline__ void operator()(const f32x4 (&acc)[2][2][4][2], const Unit& u, int wr, int wc, int fr, int fq) const {
;     ...
;                 for (int bj = 0; bj < 2; ++bj) route_in(ws, out, qscale, row, colt + bj * HALF, acc[ai][bj][m][0], acc[ai][bj][m][1]); }
.LBB0_614:
	v_pk_mul_f32 v[46:47], v[38:39], s[54:55] op_sel_hi:[1,0]
	v_pk_mul_f32 v[48:49], v[36:37], s[54:55] op_sel_hi:[1,0]
	v_pk_mul_f32 v[40:41], v[34:35], s[54:55] op_sel_hi:[1,0]
	v_pk_mul_f32 v[50:51], v[32:33], s[54:55] op_sel_hi:[1,0]
	v_cndmask_b32_e64 v43, v35, v41, s[4:5]
	v_cndmask_b32_e64 v42, v34, v40, s[4:5]
	v_cndmask_b32_e64 v41, v33, v51, s[4:5]
	v_cndmask_b32_e64 v40, v32, v50, s[4:5]
	v_cndmask_b32_e64 v39, v39, v47, s[4:5]
	v_cndmask_b32_e64 v38, v38, v46, s[4:5]
	v_cndmask_b32_e64 v37, v37, v49, s[4:5]
	v_cndmask_b32_e64 v36, v36, v48, s[4:5]
	s_and_b64 vcc, exec, s[8:9]
	s_mov_b64 s[14:15], -1
	v_cvt_pk_bf16_f32 v32, v36, v37
	v_cvt_pk_bf16_f32 v33, v38, v39
	v_cvt_pk_bf16_f32 v34, v40, v41
	v_cvt_pk_bf16_f32 v35, v42, v43
	s_cbranch_vccnz .LBB0_624
	s_and_b64 vcc, exec, s[6:7]
	s_cbranch_vccnz .LBB0_621
	s_andn2_b64 vcc, exec, s[2:3]
	s_cbranch_vccnz .LBB0_618
	v_mov_b32_e32 v47, s81
	v_mov_b32_e32 v48, s82
	v_cndmask_b32_e64 v46, v58, v60, s[12:13]
	v_cndmask_b32_e64 v136, v47, v48, s[12:13]
	s_mov_b64 s[12:13], s[94:95]
	s_mov_b64 s[14:15], s[96:97]
	v_ashrrev_i32_e32 v47, 31, v46
	v_lshlrev_b64 v[46:47], 10, v[46:47]
	s_ashr_i32 s57, s56, 31
	s_waitcnt lgkmcnt(0)
	v_lshl_add_u64 v[48:49], s[14:15], 0, v[136:137]
	v_lshl_add_u64 v[46:47], v[48:49], 0, v[46:47]
	v_lshl_add_u64 v[48:49], v[150:151], 0, s[56:57]
	v_lshl_add_u64 v[46:47], v[48:49], 1, v[46:47]
	v_lshlrev_b32_e32 v136, 2, v61
	global_store_dwordx4 v[46:47], v[32:35], off offset:256
	v_lshl_add_u64 v[46:47], s[12:13], 0, v[136:137]
	v_lshl_add_u64 v[46:47], v[46:47], 0, v[56:57]
	v_lshl_add_u64 v[46:47], v[48:49], 2, v[46:47]
	s_mov_b64 s[14:15], 0
	global_store_dwordx4 v[46:47], v[36:39], off offset:512
	global_store_dwordx4 v[46:47], v[40:43], off offset:528
.LBB0_618:
	s_andn2_b64 vcc, exec, s[14:15]
	s_cbranch_vccnz .LBB0_620
	s_mov_b64 s[12:13], s[94:95]
	s_mov_b64 s[14:15], s[96:97]
	v_mov_b32_e32 v136, v150
	s_waitcnt lgkmcnt(0)
	v_lshl_add_u64 v[36:37], s[14:15], 0, v[54:55]
	v_lshl_add_u64 v[36:37], v[136:137], 1, v[36:37]
	v_add_co_u32_e32 v36, vcc, 0xd0ff000, v36
	s_nop 1
	v_addc_co_u32_e32 v37, vcc, 0, v37, vcc
	global_store_dwordx4 v[36:37], v[32:35], off offset:1280

; __device__ __forceinline__ void route_in(unsigned char* ws, float* out, float qscale, int row, int c, f32x4 v0, f32x4 v1) {
;     ...
;     else if (pn < 6) { const int cc = c - 512; *(u32x4*)((bf16_t*)(ws + WS_XBC) + (size_t)row * 1024 + cc) = w;
.LBB0_621:
	s_andn2_b64 vcc, exec, s[14:15]
	s_cbranch_vccnz .LBB0_623
	s_mov_b64 s[12:13], s[94:95]
	s_mov_b64 s[14:15], s[96:97]
	v_mov_b32_e32 v136, v150
	s_waitcnt lgkmcnt(0)
	v_lshl_add_u64 v[36:37], s[14:15], 0, v[52:53]
	v_lshl_add_u64 v[36:37], v[136:137], 1, v[36:37]
	v_add_co_u32_e32 v36, vcc, 0x6eff000, v36
	s_nop 1
	v_addc_co_u32_e32 v37, vcc, 0, v37, vcc
	global_store_dwordx4 v[36:37], v[32:35], off offset:3328

; __device__ __forceinline__ unsigned cvt_pk_bf16(float lo, float hi) { unsigned r; asm volatile("v_cvt_pk_bf16_f32 %0, %1, %2" : "=v"(r) : "v"(lo), "v"(hi)); return r; }
; __device__ __forceinline__ void route_in(unsigned char* ws, float* out, float qscale, int row, int c, f32x4 v0, f32x4 v1) {
;     const int pn = c >> 8; const bool smp = row >= MPc; const int sb = (row - MPc) >> 6, ts = row & 63;
;     if (pn >= 6 && pn < 8) { v0 = v0 * qscale; v1 = v1 * qscale; }
;     u32x4 w; w.x = cvt_pk_bf16(v0[0], v0[1]); w.y = cvt_pk_bf16(v0[2], v0[3]); w.z = cvt_pk_bf16(v1[0], v1[1]); w.w = cvt_pk_bf16(v1[2], v1[3]);
;     if (pn < 2) { *(u32x4*)((bf16_t*)(ws + WS_Z) + (size_t)row * 512 + c) = w; }
;     else if (pn < 6) { const int cc = c - 512; *(u32x4*)((bf16_t*)(ws + WS_XBC) + (size_t)row * 1024 + cc) = w;
;         if (!smp) { const int tt = row & 4095; if (tt >= 4093) { float* p = out + O_CONVP + (size_t)((row >> 12) * 3 + tt - 4093) * 1024 + cc; *(f32x4*)p = v0; *(f32x4*)(p + 4) = v1; } }
;         else if (ts >= 61) { float* p = out + O_CONVS + (size_t)(sb * 3 + ts - 61) * 1024 + cc; *(f32x4*)p = v0; *(f32x4*)(p + 4) = v1; } }
;     else if (pn < 8) { const int cc = c - 1536; const size_t qrow = smp ? (size_t)(MPc + sb * 256 + ts) : (size_t)row; *(u32x4*)((bf16_t*)(ws + WS_Q) + qrow * 512 + cc) = w; }
;     else { const bool isk = pn < 10; const int cc = c - (isk ? 2048 : 2560);
;         bf16_t* bp = smp ? (bf16_t*)(ws + (isk ? WS_KS : WS_VS)) + (size_t)(sb * 2176 + 2048 + ts) * 512 + cc : (bf16_t*)(ws + (isk ? WS_K : WS_V)) + (size_t)row * 512 + cc;
;         *(u32x4*)bp = w;
;         float* fp = smp ? out + (isk ? O_NKS : O_NVS) + (size_t)(row - MPc) * 512 + cc : out + (isk ? O_NKP : O_NVP) + (size_t)row * 512 + cc;
;         *(f32x4*)fp = v0; *(f32x4*)(fp + 4) = v1; }
;     __device__ __forceinline__ void operator()(const f32x4 (&acc)[2][2][4][2], const Unit& u, int wr, int wc, int fr, int fq) const {
;     ...
;         for (int ai = 0; ai < 2; ++ai)
; #pragma unroll
;             for (int m = 0; m < 4; ++m) { const int row = u.pm * BM + ai * HALF + wr * 64 + m * 16 + fr;
; #pragma unroll
;                 for (int bj = 0; bj < 2; ++bj) route_in(ws, out, qscale, row, colt + bj * HALF, acc[ai][bj][m][0], acc[ai][bj][m][1]); }
.LBB0_626:
	v_or_b32_e32 v42, v112, v78
	s_nop 0
	v_add_u32_e32 v32, 0xffff8000, v42
	v_ashrrev_i32_e32 v34, 6, v32
	v_mad_u64_u32 v[44:45], s[12:13], v34, s78, v[100:101]
	v_ashrrev_i32_e32 v43, 31, v42
	v_cmp_lt_i32_e64 s[12:13], s77, v42
	v_mov_b32_e32 v35, s83
	v_mov_b32_e32 v36, s84
	v_cndmask_b32_e64 v33, v43, 0, s[12:13]
	v_cndmask_b32_e64 v32, v42, v32, s[12:13]
	v_lshlrev_b64 v[40:41], 11, v[32:33]
	v_lshl_add_u32 v32, v34, 8, v101
	v_cndmask_b32_e64 v32, v42, v32, s[12:13]
	v_ashrrev_i32_e32 v33, 31, v32
	v_lshlrev_b64 v[38:39], 10, v[32:33]
	v_pk_mul_f32 v[46:47], v[30:31], s[54:55] op_sel_hi:[1,0]
	v_pk_mul_f32 v[48:49], v[28:29], s[54:55] op_sel_hi:[1,0]
	v_pk_mul_f32 v[32:33], v[26:27], s[54:55] op_sel_hi:[1,0]
	v_pk_mul_f32 v[50:51], v[24:25], s[54:55] op_sel_hi:[1,0]
	v_cndmask_b32_e64 v45, v35, v36, s[12:13]
	v_lshlrev_b64 v[36:37], 11, v[42:43]
	v_cndmask_b32_e64 v35, v27, v33, s[4:5]
	v_cndmask_b32_e64 v34, v26, v32, s[4:5]
	v_cndmask_b32_e64 v33, v25, v51, s[4:5]
	v_cndmask_b32_e64 v32, v24, v50, s[4:5]
	v_cndmask_b32_e64 v31, v31, v47, s[4:5]
	v_cndmask_b32_e64 v30, v30, v46, s[4:5]
	v_cndmask_b32_e64 v29, v29, v49, s[4:5]
	v_cndmask_b32_e64 v28, v28, v48, s[4:5]
	s_and_b64 vcc, exec, s[8:9]
	s_mov_b64 s[14:15], -1
	v_cvt_pk_bf16_f32 v24, v28, v29
	v_cvt_pk_bf16_f32 v25, v30, v31
	v_cvt_pk_bf16_f32 v26, v32, v33
	v_cvt_pk_bf16_f32 v27, v34, v35
	s_cbranch_vccnz .LBB0_636
	s_and_b64 vcc, exec, s[6:7]
	s_cbranch_vccnz .LBB0_633
	s_andn2_b64 vcc, exec, s[2:3]
	s_cbranch_vccnz .LBB0_630
	s_mov_b64 s[88:89], s[94:95]
	s_mov_b64 s[90:91], s[96:97]
	v_cndmask_b32_e64 v48, v42, v44, s[12:13]
	v_mov_b32_e32 v47, s81
	v_mov_b32_e32 v49, s82
	v_cndmask_b32_e64 v136, v47, v49, s[12:13]
	v_ashrrev_i32_e32 v49, 31, v48
	v_add_u32_e32 v46, s56, v150
	s_waitcnt lgkmcnt(0)
	v_lshl_add_u64 v[50:51], s[90:91], 0, v[136:137]
	v_lshlrev_b64 v[48:49], 10, v[48:49]
	v_lshl_add_u64 v[48:49], v[50:51], 0, v[48:49]
	v_ashrrev_i32_e32 v47, 31, v46
	v_lshl_add_u64 v[48:49], v[46:47], 1, v[48:49]
	v_lshlrev_b32_e32 v136, 2, v45
	global_store_dwordx4 v[48:49], v[24:27], off
	v_lshl_add_u64 v[48:49], s[88:89], 0, v[136:137]
	v_lshl_add_u64 v[48:49], v[48:49], 0, v[40:41]
	v_lshl_add_u64 v[46:47], v[46:47], 2, v[48:49]
	s_mov_b64 s[14:15], 0
	global_store_dwordx4 v[46:47], v[28:31], off
	global_store_dwordx4 v[46:47], v[32:35], off offset:16
.LBB0_630:
	s_andn2_b64 vcc, exec, s[14:15]
	s_cbranch_vccnz .LBB0_632
	s_mov_b64 s[88:89], s[94:95]
	s_mov_b64 s[90:91], s[96:97]
	v_mov_b32_e32 v136, v150
	s_waitcnt lgkmcnt(0)
	v_lshl_add_u64 v[28:29], s[90:91], 0, v[38:39]
	v_lshl_add_u64 v[28:29], v[136:137], 1, v[28:29]
	v_add_co_u32_e32 v28, vcc, 0xd0ff000, v28
	s_nop 1
	v_addc_co_u32_e32 v29, vcc, 0, v29, vcc
	global_store_dwordx4 v[28:29], v[24:27], off offset:1024

; __device__ __forceinline__ void route_in(unsigned char* ws, float* out, float qscale, int row, int c, f32x4 v0, f32x4 v1) {
;     ...
;     else if (pn < 6) { const int cc = c - 512; *(u32x4*)((bf16_t*)(ws + WS_XBC) + (size_t)row * 1024 + cc) = w;
.LBB0_633:
	s_andn2_b64 vcc, exec, s[14:15]
	s_cbranch_vccnz .LBB0_635
	s_mov_b64 s[88:89], s[94:95]
	s_mov_b64 s[90:91], s[96:97]
	v_mov_b32_e32 v136, v150
	s_waitcnt lgkmcnt(0)
	v_lshl_add_u64 v[28:29], s[90:91], 0, v[36:37]
	v_lshl_add_u64 v[28:29], v[136:137], 1, v[28:29]
	v_add_co_u32_e32 v28, vcc, 0x6eff000, v28
	s_nop 1
	v_addc_co_u32_e32 v29, vcc, 0, v29, vcc
	global_store_dwordx4 v[28:29], v[24:27], off offset:3072

; __device__ __forceinline__ unsigned cvt_pk_bf16(float lo, float hi) { unsigned r; asm volatile("v_cvt_pk_bf16_f32 %0, %1, %2" : "=v"(r) : "v"(lo), "v"(hi)); return r; }
; __device__ __forceinline__ void route_in(unsigned char* ws, float* out, float qscale, int row, int c, f32x4 v0, f32x4 v1) {
;     const int pn = c >> 8; const bool smp = row >= MPc; const int sb = (row - MPc) >> 6, ts = row & 63;
;     if (pn >= 6 && pn < 8) { v0 = v0 * qscale; v1 = v1 * qscale; }
;     u32x4 w; w.x = cvt_pk_bf16(v0[0], v0[1]); w.y = cvt_pk_bf16(v0[2], v0[3]); w.z = cvt_pk_bf16(v1[0], v1[1]); w.w = cvt_pk_bf16(v1[2], v1[3]);
;     if (pn < 2) { *(u32x4*)((bf16_t*)(ws + WS_Z) + (size_t)row * 512 + c) = w; }
;     else if (pn < 6) { const int cc = c - 512; *(u32x4*)((bf16_t*)(ws + WS_XBC) + (size_t)row * 1024 + cc) = w;
;         if (!smp) { const int tt = row & 4095; if (tt >= 4093) { float* p = out + O_CONVP + (size_t)((row >> 12) * 3 + tt - 4093) * 1024 + cc; *(f32x4*)p = v0; *(f32x4*)(p + 4) = v1; } }
;         else if (ts >= 61) { float* p = out + O_CONVS + (size_t)(sb * 3 + ts - 61) * 1024 + cc; *(f32x4*)p = v0; *(f32x4*)(p + 4) = v1; } }
;     else if (pn < 8) { const int cc = c - 1536; const size_t qrow = smp ? (size_t)(MPc + sb * 256 + ts) : (size_t)row; *(u32x4*)((bf16_t*)(ws + WS_Q) + qrow * 512 + cc) = w; }
;     else { const bool isk = pn < 10; const int cc = c - (isk ? 2048 : 2560);
;         bf16_t* bp = smp ? (bf16_t*)(ws + (isk ? WS_KS : WS_VS)) + (size_t)(sb * 2176 + 2048 + ts) * 512 + cc : (bf16_t*)(ws + (isk ? WS_K : WS_V)) + (size_t)row * 512 + cc;
;         *(u32x4*)bp = w;
;         float* fp = smp ? out + (isk ? O_NKS : O_NVS) + (size_t)(row - MPc) * 512 + cc : out + (isk ? O_NKP : O_NVP) + (size_t)row * 512 + cc;
;         *(f32x4*)fp = v0; *(f32x4*)(fp + 4) = v1; }
;     __device__ __forceinline__ void operator()(const f32x4 (&acc)[2][2][4][2], const Unit& u, int wr, int wc, int fr, int fq) const {
;     ...
;                 for (int bj = 0; bj < 2; ++bj) route_in(ws, out, qscale, row, colt + bj * HALF, acc[ai][bj][m][0], acc[ai][bj][m][1]); }
.LBB0_638:
	v_pk_mul_f32 v[30:31], v[22:23], s[54:55] op_sel_hi:[1,0]
	v_pk_mul_f32 v[32:33], v[20:21], s[54:55] op_sel_hi:[1,0]
	v_pk_mul_f32 v[24:25], v[18:19], s[54:55] op_sel_hi:[1,0]
	v_pk_mul_f32 v[34:35], v[16:17], s[54:55] op_sel_hi:[1,0]
	v_cndmask_b32_e64 v27, v19, v25, s[4:5]
	v_cndmask_b32_e64 v26, v18, v24, s[4:5]
	v_cndmask_b32_e64 v25, v17, v35, s[4:5]
	v_cndmask_b32_e64 v24, v16, v34, s[4:5]
	v_cndmask_b32_e64 v23, v23, v31, s[4:5]
	v_cndmask_b32_e64 v22, v22, v30, s[4:5]
	v_cndmask_b32_e64 v21, v21, v33, s[4:5]
	v_cndmask_b32_e64 v20, v20, v32, s[4:5]
	s_and_b64 vcc, exec, s[8:9]
	s_mov_b64 s[14:15], -1
	v_cvt_pk_bf16_f32 v16, v20, v21
	v_cvt_pk_bf16_f32 v17, v22, v23
	v_cvt_pk_bf16_f32 v18, v24, v25
	v_cvt_pk_bf16_f32 v19, v26, v27
	s_cbranch_vccnz .LBB0_648
	s_and_b64 vcc, exec, s[6:7]
	s_cbranch_vccnz .LBB0_645
	s_andn2_b64 vcc, exec, s[2:3]
	s_cbranch_vccnz .LBB0_642
	v_mov_b32_e32 v31, s81
	v_mov_b32_e32 v32, s82
	v_cndmask_b32_e64 v30, v42, v44, s[12:13]
	v_cndmask_b32_e64 v136, v31, v32, s[12:13]
	s_mov_b64 s[12:13], s[94:95]
	s_mov_b64 s[14:15], s[96:97]
	v_ashrrev_i32_e32 v31, 31, v30
	v_lshlrev_b64 v[30:31], 10, v[30:31]
	s_ashr_i32 s57, s56, 31
	s_waitcnt lgkmcnt(0)
	v_lshl_add_u64 v[32:33], s[14:15], 0, v[136:137]
	v_lshl_add_u64 v[30:31], v[32:33], 0, v[30:31]
	v_lshl_add_u64 v[32:33], v[150:151], 0, s[56:57]
	v_lshl_add_u64 v[30:31], v[32:33], 1, v[30:31]
	v_lshlrev_b32_e32 v136, 2, v45
	global_store_dwordx4 v[30:31], v[16:19], off offset:256
	v_lshl_add_u64 v[30:31], s[12:13], 0, v[136:137]
	v_lshl_add_u64 v[30:31], v[30:31], 0, v[40:41]
	v_lshl_add_u64 v[30:31], v[32:33], 2, v[30:31]
	s_mov_b64 s[14:15], 0
	global_store_dwordx4 v[30:31], v[20:23], off offset:512
	global_store_dwordx4 v[30:31], v[24:27], off offset:528
.LBB0_642:
	s_andn2_b64 vcc, exec, s[14:15]
	s_cbranch_vccnz .LBB0_644
	s_mov_b64 s[12:13], s[94:95]
	s_mov_b64 s[14:15], s[96:97]
	v_mov_b32_e32 v136, v150
	s_waitcnt lgkmcnt(0)
	v_lshl_add_u64 v[20:21], s[14:15], 0, v[38:39]
	v_lshl_add_u64 v[20:21], v[136:137], 1, v[20:21]
	v_add_co_u32_e32 v20, vcc, 0xd0ff000, v20
	s_nop 1
	v_addc_co_u32_e32 v21, vcc, 0, v21, vcc
	global_store_dwordx4 v[20:21], v[16:19], off offset:1280

; __device__ __forceinline__ void route_in(unsigned char* ws, float* out, float qscale, int row, int c, f32x4 v0, f32x4 v1) {
;     ...
;     else if (pn < 6) { const int cc = c - 512; *(u32x4*)((bf16_t*)(ws + WS_XBC) + (size_t)row * 1024 + cc) = w;
.LBB0_645:
	s_andn2_b64 vcc, exec, s[14:15]
	s_cbranch_vccnz .LBB0_647
	s_mov_b64 s[12:13], s[94:95]
	s_mov_b64 s[14:15], s[96:97]
	v_mov_b32_e32 v136, v150
	s_waitcnt lgkmcnt(0)
	v_lshl_add_u64 v[20:21], s[14:15], 0, v[36:37]
	v_lshl_add_u64 v[20:21], v[136:137], 1, v[20:21]
	v_add_co_u32_e32 v20, vcc, 0x6eff000, v20
	s_nop 1
	v_addc_co_u32_e32 v21, vcc, 0, v21, vcc
	global_store_dwordx4 v[20:21], v[16:19], off offset:3328

; __device__ __forceinline__ unsigned cvt_pk_bf16(float lo, float hi) { unsigned r; asm volatile("v_cvt_pk_bf16_f32 %0, %1, %2" : "=v"(r) : "v"(lo), "v"(hi)); return r; }
; __device__ __forceinline__ void route_in(unsigned char* ws, float* out, float qscale, int row, int c, f32x4 v0, f32x4 v1) {
;     const int pn = c >> 8; const bool smp = row >= MPc; const int sb = (row - MPc) >> 6, ts = row & 63;
;     if (pn >= 6 && pn < 8) { v0 = v0 * qscale; v1 = v1 * qscale; }
;     u32x4 w; w.x = cvt_pk_bf16(v0[0], v0[1]); w.y = cvt_pk_bf16(v0[2], v0[3]); w.z = cvt_pk_bf16(v1[0], v1[1]); w.w = cvt_pk_bf16(v1[2], v1[3]);
;     if (pn < 2) { *(u32x4*)((bf16_t*)(ws + WS_Z) + (size_t)row * 512 + c) = w; }
;     else if (pn < 6) { const int cc = c - 512; *(u32x4*)((bf16_t*)(ws + WS_XBC) + (size_t)row * 1024 + cc) = w;
;         if (!smp) { const int tt = row & 4095; if (tt >= 4093) { float* p = out + O_CONVP + (size_t)((row >> 12) * 3 + tt - 4093) * 1024 + cc; *(f32x4*)p = v0; *(f32x4*)(p + 4) = v1; } }
;         else if (ts >= 61) { float* p = out + O_CONVS + (size_t)(sb * 3 + ts - 61) * 1024 + cc; *(f32x4*)p = v0; *(f32x4*)(p + 4) = v1; } }
;     else if (pn < 8) { const int cc = c - 1536; const size_t qrow = smp ? (size_t)(MPc + sb * 256 + ts) : (size_t)row; *(u32x4*)((bf16_t*)(ws + WS_Q) + qrow * 512 + cc) = w; }
;     else { const bool isk = pn < 10; const int cc = c - (isk ? 2048 : 2560);
;         bf16_t* bp = smp ? (bf16_t*)(ws + (isk ? WS_KS : WS_VS)) + (size_t)(sb * 2176 + 2048 + ts) * 512 + cc : (bf16_t*)(ws + (isk ? WS_K : WS_V)) + (size_t)row * 512 + cc;
;         *(u32x4*)bp = w;
;         float* fp = smp ? out + (isk ? O_NKS : O_NVS) + (size_t)(row - MPc) * 512 + cc : out + (isk ? O_NKP : O_NVP) + (size_t)row * 512 + cc;
;         *(f32x4*)fp = v0; *(f32x4*)(fp + 4) = v1; }
;     __device__ __forceinline__ void operator()(const f32x4 (&acc)[2][2][4][2], const Unit& u, int wr, int wc, int fr, int fq) const {
;     ...
;         for (int ai = 0; ai < 2; ++ai)
; #pragma unroll
;             for (int m = 0; m < 4; ++m) { const int row = u.pm * BM + ai * HALF + wr * 64 + m * 16 + fr;
; #pragma unroll
;                 for (int bj = 0; bj < 2; ++bj) route_in(ws, out, qscale, row, colt + bj * HALF, acc[ai][bj][m][0], acc[ai][bj][m][1]); }
.LBB0_650:
	s_nop 1
	v_ashrrev_i32_e32 v16, 12, v78
	v_mul_lo_u32 v16, v16, 3
	v_or_b32_e32 v30, v85, v78
	v_add_u32_e32 v18, 0xfffff003, v16
	v_add_u32_e32 v16, 0xffff8000, v30
	v_ashrrev_i32_e32 v31, 31, v30
	v_cmp_lt_i32_e64 s[16:17], s77, v30
	v_ashrrev_i32_e32 v19, 6, v16
	v_mad_u64_u32 v[32:33], s[14:15], v19, s78, v[84:85]
	v_cndmask_b32_e64 v17, v31, 0, s[16:17]
	v_cndmask_b32_e64 v16, v30, v16, s[16:17]
	v_lshlrev_b64 v[28:29], 11, v[16:17]
	v_lshl_add_u32 v16, v19, 8, v87
	v_cndmask_b32_e64 v16, v30, v16, s[16:17]
	v_ashrrev_i32_e32 v17, 31, v16
	v_lshlrev_b64 v[26:27], 10, v[16:17]
	v_bitop3_b32 v16, v85, s79, v78 bitop3:0xc8
	v_cmp_lt_u32_e64 s[14:15], s80, v16
	v_add_u32_e32 v16, v18, v16
	v_ashrrev_i32_e32 v17, 31, v16
	v_lshlrev_b64 v[22:23], 12, v[16:17]
	v_mad_u64_u32 v[16:17], s[58:59], v19, 3, v[86:87]
	v_mov_b32_e32 v20, s83
	v_mov_b32_e32 v21, s84
	v_ashrrev_i32_e32 v17, 31, v16
	v_cndmask_b32_e64 v33, v20, v21, s[16:17]
	v_lshlrev_b64 v[20:21], 12, v[16:17]
	v_pk_mul_f32 v[34:35], v[14:15], s[54:55] op_sel_hi:[1,0]
	v_pk_mul_f32 v[36:37], v[12:13], s[54:55] op_sel_hi:[1,0]
	v_pk_mul_f32 v[16:17], v[10:11], s[54:55] op_sel_hi:[1,0]
	v_pk_mul_f32 v[38:39], v[8:9], s[54:55] op_sel_hi:[1,0]
	v_cmp_gt_i32_e64 s[12:13], s72, v30
	v_lshlrev_b64 v[24:25], 11, v[30:31]
	v_cndmask_b32_e64 v19, v11, v17, s[4:5]
	v_cndmask_b32_e64 v18, v10, v16, s[4:5]
	v_cndmask_b32_e64 v17, v9, v39, s[4:5]
	v_cndmask_b32_e64 v16, v8, v38, s[4:5]
	v_cndmask_b32_e64 v15, v15, v35, s[4:5]
	v_cndmask_b32_e64 v14, v14, v34, s[4:5]
	v_cndmask_b32_e64 v13, v13, v37, s[4:5]
	v_cndmask_b32_e64 v12, v12, v36, s[4:5]
	s_and_b64 vcc, exec, s[8:9]
	s_mov_b64 s[58:59], -1
	v_cvt_pk_bf16_f32 v8, v12, v13
	v_cvt_pk_bf16_f32 v9, v14, v15
	v_cvt_pk_bf16_f32 v10, v16, v17
	v_cvt_pk_bf16_f32 v11, v18, v19
	s_cbranch_vccnz .LBB0_668
	s_and_b64 vcc, exec, s[6:7]
	s_cbranch_vccnz .LBB0_657
	s_andn2_b64 vcc, exec, s[2:3]
	s_cbranch_vccnz .LBB0_654
	v_readlane_b32 s58, v254, 11
	v_readlane_b32 s59, v254, 12
	s_mov_b64 s[84:85], s[94:95]
	s_mov_b64 s[86:87], s[96:97]
	v_cndmask_b32_e64 v36, v30, v32, s[16:17]
	v_mov_b32_e32 v35, s81
	v_mov_b32_e32 v37, s82
	v_cndmask_b32_e64 v136, v35, v37, s[16:17]
	v_ashrrev_i32_e32 v37, 31, v36
	v_add_u32_e32 v34, s56, v150
	s_waitcnt lgkmcnt(0)
	v_lshl_add_u64 v[38:39], s[86:87], 0, v[136:137]
	v_lshlrev_b64 v[36:37], 10, v[36:37]
	v_lshl_add_u64 v[36:37], v[38:39], 0, v[36:37]
	v_ashrrev_i32_e32 v35, 31, v34
	v_lshl_add_u64 v[36:37], v[34:35], 1, v[36:37]
	v_lshlrev_b32_e32 v136, 2, v33
	global_store_dwordx4 v[36:37], v[8:11], off
	v_lshl_add_u64 v[36:37], s[84:85], 0, v[136:137]
	v_lshl_add_u64 v[36:37], v[36:37], 0, v[28:29]
	v_lshl_add_u64 v[34:35], v[34:35], 2, v[36:37]
	s_mov_b64 s[58:59], 0
	global_store_dwordx4 v[34:35], v[12:15], off
	global_store_dwordx4 v[34:35], v[16:19], off offset:16
.LBB0_654:
	s_andn2_b64 vcc, exec, s[58:59]
	s_cbranch_vccnz .LBB0_656
	v_readlane_b32 s58, v254, 11
	v_readlane_b32 s59, v254, 12
	s_mov_b64 s[84:85], s[94:95]
	s_mov_b64 s[86:87], s[96:97]
	v_mov_b32_e32 v136, v150
	s_waitcnt lgkmcnt(0)
	v_lshl_add_u64 v[34:35], s[86:87], 0, v[26:27]
	v_lshl_add_u64 v[34:35], v[136:137], 1, v[34:35]
	v_add_co_u32_e32 v34, vcc, 0xd0ff000, v34
	s_nop 1
	v_addc_co_u32_e32 v35, vcc, 0, v35, vcc
	global_store_dwordx4 v[34:35], v[8:11], off offset:1024

; __device__ __forceinline__ unsigned cvt_pk_bf16(float lo, float hi) { unsigned r; asm volatile("v_cvt_pk_bf16_f32 %0, %1, %2" : "=v"(r) : "v"(lo), "v"(hi)); return r; }
; __device__ __forceinline__ void route_in(unsigned char* ws, float* out, float qscale, int row, int c, f32x4 v0, f32x4 v1) {
;     const int pn = c >> 8; const bool smp = row >= MPc; const int sb = (row - MPc) >> 6, ts = row & 63;
;     if (pn >= 6 && pn < 8) { v0 = v0 * qscale; v1 = v1 * qscale; }
;     u32x4 w; w.x = cvt_pk_bf16(v0[0], v0[1]); w.y = cvt_pk_bf16(v0[2], v0[3]); w.z = cvt_pk_bf16(v1[0], v1[1]); w.w = cvt_pk_bf16(v1[2], v1[3]);
;     if (pn < 2) { *(u32x4*)((bf16_t*)(ws + WS_Z) + (size_t)row * 512 + c) = w; }
;     else if (pn < 6) { const int cc = c - 512; *(u32x4*)((bf16_t*)(ws + WS_XBC) + (size_t)row * 1024 + cc) = w;
;         if (!smp) { const int tt = row & 4095; if (tt >= 4093) { float* p = out + O_CONVP + (size_t)((row >> 12) * 3 + tt - 4093) * 1024 + cc; *(f32x4*)p = v0; *(f32x4*)(p + 4) = v1; } }
;         else if (ts >= 61) { float* p = out + O_CONVS + (size_t)(sb * 3 + ts - 61) * 1024 + cc; *(f32x4*)p = v0; *(f32x4*)(p + 4) = v1; } }
;     else if (pn < 8) { const int cc = c - 1536; const size_t qrow = smp ? (size_t)(MPc + sb * 256 + ts) : (size_t)row; *(u32x4*)((bf16_t*)(ws + WS_Q) + qrow * 512 + cc) = w; }
;     else { const bool isk = pn < 10; const int cc = c - (isk ? 2048 : 2560);
;         bf16_t* bp = smp ? (bf16_t*)(ws + (isk ? WS_KS : WS_VS)) + (size_t)(sb * 2176 + 2048 + ts) * 512 + cc : (bf16_t*)(ws + (isk ? WS_K : WS_V)) + (size_t)row * 512 + cc;
;         *(u32x4*)bp = w;
;         float* fp = smp ? out + (isk ? O_NKS : O_NVS) + (size_t)(row - MPc) * 512 + cc : out + (isk ? O_NKP : O_NVP) + (size_t)row * 512 + cc;
;         *(f32x4*)fp = v0; *(f32x4*)(fp + 4) = v1; }
.LBB0_673:
	s_and_b64 vcc, exec, s[6:7]
	s_cbranch_vccnz .LBB0_679
	s_andn2_b64 vcc, exec, s[2:3]
	s_mov_b64 s[2:3], -1
	s_cbranch_vccnz .LBB0_676
	s_mov_b64 s[4:5], s[94:95]
	s_mov_b64 s[6:7], s[96:97]
	v_cndmask_b32_e64 v14, v30, v32, s[16:17]
	v_mov_b32_e32 v15, s81
	v_mov_b32_e32 v16, s82
	v_cndmask_b32_e64 v136, v15, v16, s[16:17]
	v_ashrrev_i32_e32 v15, 31, v14
	s_waitcnt lgkmcnt(0)
	v_lshl_add_u64 v[16:17], s[6:7], 0, v[136:137]
	v_lshlrev_b64 v[14:15], 10, v[14:15]
	s_ashr_i32 s57, s56, 31
	v_lshl_add_u64 v[14:15], v[16:17], 0, v[14:15]
	v_lshl_add_u64 v[16:17], v[150:151], 0, s[56:57]
	v_lshl_add_u64 v[14:15], v[16:17], 1, v[14:15]
	v_lshlrev_b32_e32 v136, 2, v33
	global_store_dwordx4 v[14:15], v[0:3], off offset:256
	v_lshl_add_u64 v[14:15], s[4:5], 0, v[136:137]
	v_lshl_add_u64 v[14:15], v[14:15], 0, v[28:29]
	v_lshl_add_u64 v[14:15], v[16:17], 2, v[14:15]
	s_mov_b64 s[2:3], 0
	global_store_dwordx4 v[14:15], v[4:7], off offset:512
	global_store_dwordx4 v[14:15], v[8:11], off offset:528
.LBB0_676:
	s_andn2_b64 vcc, exec, s[2:3]
	s_cbranch_vccnz .LBB0_678
	s_mov_b64 s[4:5], s[94:95]
	s_mov_b64 s[6:7], s[96:97]
	v_mov_b32_e32 v136, v150
	s_waitcnt lgkmcnt(0)
	v_lshl_add_u64 v[14:15], s[6:7], 0, v[26:27]
	v_lshl_add_u64 v[14:15], v[136:137], 1, v[14:15]
	v_add_co_u32_e32 v14, vcc, 0xd0ff000, v14
	s_nop 1
	v_addc_co_u32_e32 v15, vcc, 0, v15, vcc
	global_store_dwordx4 v[14:15], v[0:3], off offset:1280
